# box filter (phase 3b) rewritten by hand as one two-trip loop: window sums unrolled with the four tokens' LDS reads of a step in flight together, adds masked by exec; same sums, exact quotients
# speedup vs baseline: 1.0005x; 1.0005x over previous
; #define LAS __attribute__((address_space(3)))
; __device__ __forceinline__ int opaque_tid() { int t = (int)threadIdx.x; asm volatile("" : "+v"(t)); return t; }
; __device__ __forceinline__ float bf_lo(unsigned w) { return __uint_as_float(w << 16); }
; __device__ __forceinline__ float bf_hi(unsigned w) { return __uint_as_float(w & 0xffff0000u); }
; __device__ void boxfilter_unit(const Params& p, LAS unsigned char* lds, int u) {
;     const int tid = opaque_tid();
;     const int b = u >> 6, g = (u >> 4) & 3, cb = u & 15; const int hw = 1 << g;
;     LAS float* X = (LAS float*)lds; LAS float* Y = X + 2048 * 8;
;     const bf16_t* src = (const bf16_t*)(p.ws + OFF_P) + (size_t)(b * 64 + g * 16 + cb) * 2048 * 8;
;     bf16_t* dst = (bf16_t*)(p.ws + OFF_MX) + (size_t)(b * 2048) * 512 + g * 128 + cb * 8;
; #pragma unroll
;     for (int i = 0; i < 4; ++i) { const int tok = tid + 512 * i; const u32x4 v = __builtin_nontemporal_load((const u32x4*)(src + (size_t)tok * 8));
;         *(LAS f32x4*)(X + tok * 8) = (f32x4){bf_lo(v.x), bf_hi(v.x), bf_lo(v.y), bf_hi(v.y)}; *(LAS f32x4*)(X + tok * 8 + 4) = (f32x4){bf_lo(v.z), bf_hi(v.z), bf_lo(v.w), bf_hi(v.w)}; }
;     __syncthreads();
;     for (int i = 0; i < 4; ++i) { const int tok = tid + 512 * i; const int r = tok >> 6, c = tok & 63; const int lo = max(r - hw, 0), hi = min(r + hw, 32);
;         f32x4 s0 = (f32x4){0.f, 0.f, 0.f, 0.f}, s1 = s0;
; __device__ __forceinline__ void run_phase(const Params& p, LAS unsigned char* lds, int ph) {
;     ...
;         { const int c3 = blockIdx.x, xcd = c3 & 7, sl = c3 >> 3;
;           passA(p, lds, (xcd * 8 + (sl >> 2)) * 4 + (sl & 3));
;           const int G = (sl >> 2) * 8 + xcd, mem = sl & 3;
;           boxfilter_unit(p, lds, G * 4 + mem); boxfilter_unit(p, lds, (127 - G) * 4 + mem); }
.LBB0_401:
	s_cbranch_execz .LBB0_392
	s_barrier
	s_and_b32 s0, s2, 7
	s_lshr_b32 s1, s2, 3
	s_and_b32 s3, s1, 3
	s_lshr_b32 s1, s1, 2
	s_lshl_b32 s1, s1, 3
	s_or_b32 s1, s1, s0
	s_lshl_b32 s4, s1, 2
	s_or_b32 s4, s4, s3
	s_sub_u32 s5, 0x7f, s1
	s_lshl_b32 s5, s5, 2
	s_or_b32 s5, s5, s3
	v_readlane_b32 s38, v254, 22
	v_readlane_b32 s39, v254, 23
	s_add_u32 s41, s70, 0xac00000
	s_addc_u32 s94, s71, 0
	v_and_b32_e32 v10, 63, v224
	v_lshrrev_b32_e32 v11, 6, v224
	v_lshlrev_b32_e32 v12, 5, v224
	v_lshlrev_b32_e32 v4, 4, v224
	v_readfirstlane_b32 s6, v11
	v_add_u32_e32 v5, 0x2000, v4
	v_add_u32_e32 v6, 0x4000, v4
	v_add_u32_e32 v7, 0x6000, v4
	v_lshlrev_b32_e32 v136, 10, v224
	v_add_u32_e32 v137, 0x80000, v136
	v_add_u32_e32 v138, 0x100000, v136
	v_add_u32_e32 v139, 0x180000, v136
	v_lshlrev_b32_e32 v15, 5, v10
	s_mov_b32 s7, 0
.Lbox_unit:
	s_cmp_eq_u32 s7, 0
	s_cselect_b32 s8, s4, s5
	s_bfe_u32 s9, s8, 0x20004
	s_lshl_b32 s10, 1, s9
	s_lshl_b32 s11, s10, 1
	s_lshl_b32 s25, s8, 15
	s_add_u32 s25, s25, 0x9c00000
	s_add_u32 s26, s70, s25
	s_addc_u32 s27, s71, 0
	global_load_dwordx4 v[16:19], v4, s[26:27] nt
	global_load_dwordx4 v[20:23], v5, s[26:27] nt
	global_load_dwordx4 v[24:27], v6, s[26:27] nt
	global_load_dwordx4 v[28:31], v7, s[26:27] nt
	s_lshr_b32 s25, s8, 6
	s_lshl_b32 s25, s25, 21
	s_lshl_b32 s28, s9, 8
	s_add_u32 s25, s25, s28
	s_and_b32 s28, s8, 15
	s_lshl_b32 s28, s28, 4
	s_add_u32 s25, s25, s28
	s_add_u32 s28, s41, s25
	s_addc_u32 s29, s94, 0
	s_add_u32 s54, s6, 0
	s_sub_i32 s55, s54, s10
	s_max_i32 s55, s55, 0
	s_add_i32 s56, s54, s10
	s_min_i32 s56, s56, 32
	s_sub_u32 s58, s56, s55
	s_lshl_b32 s55, s55, 11
	v_add_u32_e32 v106, s55, v15
	s_add_u32 s54, s6, 8
	s_sub_i32 s55, s54, s10
	s_max_i32 s55, s55, 0
	s_add_i32 s56, s54, s10
	s_min_i32 s56, s56, 32
	s_sub_u32 s59, s56, s55
	s_lshl_b32 s55, s55, 11
	v_add_u32_e32 v107, s55, v15
	s_add_u32 s54, s6, 16
	s_sub_i32 s55, s54, s10
	s_max_i32 s55, s55, 0
	s_add_i32 s56, s54, s10
	s_min_i32 s56, s56, 32
	s_sub_u32 s60, s56, s55
	s_lshl_b32 s55, s55, 11
	v_add_u32_e32 v108, s55, v15
	s_add_u32 s54, s6, 24
	s_sub_i32 s55, s54, s10
	s_max_i32 s55, s55, 0
	s_add_i32 s56, s54, s10
	s_min_i32 s56, s56, 32
	s_sub_u32 s61, s56, s55
	s_lshl_b32 s55, s55, 11
	v_add_u32_e32 v109, s55, v15
	s_waitcnt vmcnt(3)
	v_lshlrev_b32_e32 v32, 16, v16
	v_and_b32_e32 v33, 0xffff0000, v16
	v_lshlrev_b32_e32 v34, 16, v17
	v_and_b32_e32 v35, 0xffff0000, v17
	v_lshlrev_b32_e32 v36, 16, v18
	v_and_b32_e32 v37, 0xffff0000, v18
	v_lshlrev_b32_e32 v38, 16, v19
	v_and_b32_e32 v39, 0xffff0000, v19
	ds_write_b128 v12, v[32:35]
	ds_write_b128 v12, v[36:39] offset:16
	s_waitcnt vmcnt(2)
	v_lshlrev_b32_e32 v32, 16, v20
	v_and_b32_e32 v33, 0xffff0000, v20
	v_lshlrev_b32_e32 v34, 16, v21
	v_and_b32_e32 v35, 0xffff0000, v21
	v_lshlrev_b32_e32 v36, 16, v22
	v_and_b32_e32 v37, 0xffff0000, v22
	v_lshlrev_b32_e32 v38, 16, v23
	v_and_b32_e32 v39, 0xffff0000, v23
	ds_write_b128 v12, v[32:35] offset:16384
	ds_write_b128 v12, v[36:39] offset:16400
	s_waitcnt vmcnt(1)
	v_lshlrev_b32_e32 v32, 16, v24
	v_and_b32_e32 v33, 0xffff0000, v24
	v_lshlrev_b32_e32 v34, 16, v25
	v_and_b32_e32 v35, 0xffff0000, v25
	v_lshlrev_b32_e32 v36, 16, v26
	v_and_b32_e32 v37, 0xffff0000, v26
	v_lshlrev_b32_e32 v38, 16, v27
	v_and_b32_e32 v39, 0xffff0000, v27
	ds_write_b128 v12, v[32:35] offset:32768
	ds_write_b128 v12, v[36:39] offset:32784
	s_waitcnt vmcnt(0)
	v_lshlrev_b32_e32 v32, 16, v28
	v_and_b32_e32 v33, 0xffff0000, v28
	v_lshlrev_b32_e32 v34, 16, v29
	v_and_b32_e32 v35, 0xffff0000, v29
	v_lshlrev_b32_e32 v36, 16, v30
	v_and_b32_e32 v37, 0xffff0000, v30
	v_lshlrev_b32_e32 v38, 16, v31
	v_and_b32_e32 v39, 0xffff0000, v31
	ds_write_b128 v12, v[32:35] offset:49152
	ds_write_b128 v12, v[36:39] offset:49168
	v_mov_b32_e32 v40, 0
	v_mov_b32_e32 v41, 0
	v_mov_b32_e32 v42, 0
	v_mov_b32_e32 v43, 0
	v_mov_b32_e32 v44, 0
	v_mov_b32_e32 v45, 0
	v_mov_b32_e32 v46, 0
	v_mov_b32_e32 v47, 0
	v_mov_b32_e32 v48, 0
	v_mov_b32_e32 v49, 0
	v_mov_b32_e32 v50, 0
	v_mov_b32_e32 v51, 0
	v_mov_b32_e32 v52, 0
	v_mov_b32_e32 v53, 0
	v_mov_b32_e32 v54, 0
	v_mov_b32_e32 v55, 0
	v_mov_b32_e32 v56, 0
	v_mov_b32_e32 v57, 0
	v_mov_b32_e32 v58, 0
	v_mov_b32_e32 v59, 0
	v_mov_b32_e32 v60, 0
	v_mov_b32_e32 v61, 0
	v_mov_b32_e32 v62, 0
	v_mov_b32_e32 v63, 0
	v_mov_b32_e32 v64, 0
	v_mov_b32_e32 v65, 0
	v_mov_b32_e32 v66, 0
	v_mov_b32_e32 v67, 0
	v_mov_b32_e32 v68, 0
	v_mov_b32_e32 v69, 0
	v_mov_b32_e32 v70, 0
	v_mov_b32_e32 v71, 0
	s_waitcnt lgkmcnt(0)
	s_barrier
; #define LAS __attribute__((address_space(3)))
; __device__ void boxfilter_unit(const Params& p, LAS unsigned char* lds, int u) {
;     ...
;     for (int i = 0; i < 4; ++i) { const int tok = tid + 512 * i; const int r = tok >> 6, c = tok & 63; const int lo = max(r - hw, 0), hi = min(r + hw, 32);
;         f32x4 s0 = (f32x4){0.f, 0.f, 0.f, 0.f}, s1 = s0;
;         for (int rr = lo; rr < hi; ++rr) { s0 += *(const LAS f32x4*)(X + (rr * 64 + c) * 8); s1 += *(const LAS f32x4*)(X + (rr * 64 + c) * 8 + 4); }
;         const float cnt = (float)(hi - lo);
;         *(LAS f32x4*)(Y + tok * 8) = s0 / cnt; *(LAS f32x4*)(Y + tok * 8 + 4) = s1 / cnt; }
	ds_read_b128 v[72:75], v106
	ds_read_b128 v[76:79], v106 offset:16
	ds_read_b128 v[80:83], v107
	ds_read_b128 v[84:87], v107 offset:16
	ds_read_b128 v[88:91], v108
	ds_read_b128 v[92:95], v108 offset:16
	ds_read_b128 v[96:99], v109
	ds_read_b128 v[100:103], v109 offset:16
	s_waitcnt lgkmcnt(6)
	s_cmp_gt_u32 s58, 0
	s_cselect_b64 exec, -1, 0
	v_pk_add_f32 v[40:41], v[40:41], v[72:73]
	v_pk_add_f32 v[42:43], v[42:43], v[74:75]
	v_pk_add_f32 v[44:45], v[44:45], v[76:77]
	v_pk_add_f32 v[46:47], v[46:47], v[78:79]
	s_waitcnt lgkmcnt(4)
	s_cmp_gt_u32 s59, 0
	s_cselect_b64 exec, -1, 0
	v_pk_add_f32 v[48:49], v[48:49], v[80:81]
	v_pk_add_f32 v[50:51], v[50:51], v[82:83]
	v_pk_add_f32 v[52:53], v[52:53], v[84:85]
	v_pk_add_f32 v[54:55], v[54:55], v[86:87]
	s_waitcnt lgkmcnt(2)
	s_cmp_gt_u32 s60, 0
	s_cselect_b64 exec, -1, 0
	v_pk_add_f32 v[56:57], v[56:57], v[88:89]
	v_pk_add_f32 v[58:59], v[58:59], v[90:91]
	v_pk_add_f32 v[60:61], v[60:61], v[92:93]
	v_pk_add_f32 v[62:63], v[62:63], v[94:95]
	s_waitcnt lgkmcnt(0)
	s_cmp_gt_u32 s61, 0
	s_cselect_b64 exec, -1, 0
	v_pk_add_f32 v[64:65], v[64:65], v[96:97]
	v_pk_add_f32 v[66:67], v[66:67], v[98:99]
	v_pk_add_f32 v[68:69], v[68:69], v[100:101]
	v_pk_add_f32 v[70:71], v[70:71], v[102:103]
	s_mov_b64 exec, -1
	ds_read_b128 v[72:75], v106 offset:2048
	ds_read_b128 v[76:79], v106 offset:2064
	ds_read_b128 v[80:83], v107 offset:2048
	ds_read_b128 v[84:87], v107 offset:2064
	ds_read_b128 v[88:91], v108 offset:2048
	ds_read_b128 v[92:95], v108 offset:2064
	ds_read_b128 v[96:99], v109 offset:2048
	ds_read_b128 v[100:103], v109 offset:2064
	s_waitcnt lgkmcnt(6)
	s_cmp_gt_u32 s58, 1
	s_cselect_b64 exec, -1, 0
	v_pk_add_f32 v[40:41], v[40:41], v[72:73]
	v_pk_add_f32 v[42:43], v[42:43], v[74:75]
	v_pk_add_f32 v[44:45], v[44:45], v[76:77]
	v_pk_add_f32 v[46:47], v[46:47], v[78:79]
	s_waitcnt lgkmcnt(4)
	s_cmp_gt_u32 s59, 1
	s_cselect_b64 exec, -1, 0
	v_pk_add_f32 v[48:49], v[48:49], v[80:81]
	v_pk_add_f32 v[50:51], v[50:51], v[82:83]
	v_pk_add_f32 v[52:53], v[52:53], v[84:85]
	v_pk_add_f32 v[54:55], v[54:55], v[86:87]
	s_waitcnt lgkmcnt(2)
	s_cmp_gt_u32 s60, 1
	s_cselect_b64 exec, -1, 0
	v_pk_add_f32 v[56:57], v[56:57], v[88:89]
	v_pk_add_f32 v[58:59], v[58:59], v[90:91]
	v_pk_add_f32 v[60:61], v[60:61], v[92:93]
	v_pk_add_f32 v[62:63], v[62:63], v[94:95]
	s_waitcnt lgkmcnt(0)
	s_cmp_gt_u32 s61, 1
	s_cselect_b64 exec, -1, 0
	v_pk_add_f32 v[64:65], v[64:65], v[96:97]
	v_pk_add_f32 v[66:67], v[66:67], v[98:99]
	v_pk_add_f32 v[68:69], v[68:69], v[100:101]
	v_pk_add_f32 v[70:71], v[70:71], v[102:103]
	s_mov_b64 exec, -1
	s_cmp_le_u32 s11, 2
	s_cbranch_scc1 .Lbox_p1_done
	ds_read_b128 v[72:75], v106 offset:4096
	ds_read_b128 v[76:79], v106 offset:4112
	ds_read_b128 v[80:83], v107 offset:4096
	ds_read_b128 v[84:87], v107 offset:4112
	ds_read_b128 v[88:91], v108 offset:4096
	ds_read_b128 v[92:95], v108 offset:4112
	ds_read_b128 v[96:99], v109 offset:4096
	ds_read_b128 v[100:103], v109 offset:4112
	s_waitcnt lgkmcnt(6)
	s_cmp_gt_u32 s58, 2
	s_cselect_b64 exec, -1, 0
	v_pk_add_f32 v[40:41], v[40:41], v[72:73]
	v_pk_add_f32 v[42:43], v[42:43], v[74:75]
	v_pk_add_f32 v[44:45], v[44:45], v[76:77]
	v_pk_add_f32 v[46:47], v[46:47], v[78:79]
	s_waitcnt lgkmcnt(4)
	s_cmp_gt_u32 s59, 2
	s_cselect_b64 exec, -1, 0
	v_pk_add_f32 v[48:49], v[48:49], v[80:81]
	v_pk_add_f32 v[50:51], v[50:51], v[82:83]
	v_pk_add_f32 v[52:53], v[52:53], v[84:85]
	v_pk_add_f32 v[54:55], v[54:55], v[86:87]
	s_waitcnt lgkmcnt(2)
	s_cmp_gt_u32 s60, 2
	s_cselect_b64 exec, -1, 0
	v_pk_add_f32 v[56:57], v[56:57], v[88:89]
	v_pk_add_f32 v[58:59], v[58:59], v[90:91]
	v_pk_add_f32 v[60:61], v[60:61], v[92:93]
	v_pk_add_f32 v[62:63], v[62:63], v[94:95]
	s_waitcnt lgkmcnt(0)
	s_cmp_gt_u32 s61, 2
	s_cselect_b64 exec, -1, 0
	v_pk_add_f32 v[64:65], v[64:65], v[96:97]
	v_pk_add_f32 v[66:67], v[66:67], v[98:99]
	v_pk_add_f32 v[68:69], v[68:69], v[100:101]
	v_pk_add_f32 v[70:71], v[70:71], v[102:103]
	s_mov_b64 exec, -1
	ds_read_b128 v[72:75], v106 offset:6144
	ds_read_b128 v[76:79], v106 offset:6160
	ds_read_b128 v[80:83], v107 offset:6144
	ds_read_b128 v[84:87], v107 offset:6160
	ds_read_b128 v[88:91], v108 offset:6144
	ds_read_b128 v[92:95], v108 offset:6160
	ds_read_b128 v[96:99], v109 offset:6144
	ds_read_b128 v[100:103], v109 offset:6160
	s_waitcnt lgkmcnt(6)
	s_cmp_gt_u32 s58, 3
	s_cselect_b64 exec, -1, 0
	v_pk_add_f32 v[40:41], v[40:41], v[72:73]
	v_pk_add_f32 v[42:43], v[42:43], v[74:75]
	v_pk_add_f32 v[44:45], v[44:45], v[76:77]
	v_pk_add_f32 v[46:47], v[46:47], v[78:79]
	s_waitcnt lgkmcnt(4)
	s_cmp_gt_u32 s59, 3
	s_cselect_b64 exec, -1, 0
	v_pk_add_f32 v[48:49], v[48:49], v[80:81]
	v_pk_add_f32 v[50:51], v[50:51], v[82:83]
	v_pk_add_f32 v[52:53], v[52:53], v[84:85]
	v_pk_add_f32 v[54:55], v[54:55], v[86:87]
	s_waitcnt lgkmcnt(2)
	s_cmp_gt_u32 s60, 3
	s_cselect_b64 exec, -1, 0
	v_pk_add_f32 v[56:57], v[56:57], v[88:89]
	v_pk_add_f32 v[58:59], v[58:59], v[90:91]
	v_pk_add_f32 v[60:61], v[60:61], v[92:93]
	v_pk_add_f32 v[62:63], v[62:63], v[94:95]
	s_waitcnt lgkmcnt(0)
	s_cmp_gt_u32 s61, 3
	s_cselect_b64 exec, -1, 0
	v_pk_add_f32 v[64:65], v[64:65], v[96:97]
	v_pk_add_f32 v[66:67], v[66:67], v[98:99]
	v_pk_add_f32 v[68:69], v[68:69], v[100:101]
	v_pk_add_f32 v[70:71], v[70:71], v[102:103]
	s_mov_b64 exec, -1
	s_cmp_le_u32 s11, 4
	s_cbranch_scc1 .Lbox_p1_done
; #define LAS __attribute__((address_space(3)))
; __device__ void boxfilter_unit(const Params& p, LAS unsigned char* lds, int u) {
;     ...
;     for (int i = 0; i < 4; ++i) { const int tok = tid + 512 * i; const int r = tok >> 6, c = tok & 63; const int lo = max(r - hw, 0), hi = min(r + hw, 32);
;         f32x4 s0 = (f32x4){0.f, 0.f, 0.f, 0.f}, s1 = s0;
;         for (int rr = lo; rr < hi; ++rr) { s0 += *(const LAS f32x4*)(X + (rr * 64 + c) * 8); s1 += *(const LAS f32x4*)(X + (rr * 64 + c) * 8 + 4); }
;         const float cnt = (float)(hi - lo);
;         *(LAS f32x4*)(Y + tok * 8) = s0 / cnt; *(LAS f32x4*)(Y + tok * 8 + 4) = s1 / cnt; }
	ds_read_b128 v[72:75], v106 offset:8192
	ds_read_b128 v[76:79], v106 offset:8208
	ds_read_b128 v[80:83], v107 offset:8192
	ds_read_b128 v[84:87], v107 offset:8208
	ds_read_b128 v[88:91], v108 offset:8192
	ds_read_b128 v[92:95], v108 offset:8208
	ds_read_b128 v[96:99], v109 offset:8192
	ds_read_b128 v[100:103], v109 offset:8208
	s_waitcnt lgkmcnt(6)
	s_cmp_gt_u32 s58, 4
	s_cselect_b64 exec, -1, 0
	v_pk_add_f32 v[40:41], v[40:41], v[72:73]
	v_pk_add_f32 v[42:43], v[42:43], v[74:75]
	v_pk_add_f32 v[44:45], v[44:45], v[76:77]
	v_pk_add_f32 v[46:47], v[46:47], v[78:79]
	s_waitcnt lgkmcnt(4)
	s_cmp_gt_u32 s59, 4
	s_cselect_b64 exec, -1, 0
	v_pk_add_f32 v[48:49], v[48:49], v[80:81]
	v_pk_add_f32 v[50:51], v[50:51], v[82:83]
	v_pk_add_f32 v[52:53], v[52:53], v[84:85]
	v_pk_add_f32 v[54:55], v[54:55], v[86:87]
	s_waitcnt lgkmcnt(2)
	s_cmp_gt_u32 s60, 4
	s_cselect_b64 exec, -1, 0
	v_pk_add_f32 v[56:57], v[56:57], v[88:89]
	v_pk_add_f32 v[58:59], v[58:59], v[90:91]
	v_pk_add_f32 v[60:61], v[60:61], v[92:93]
	v_pk_add_f32 v[62:63], v[62:63], v[94:95]
	s_waitcnt lgkmcnt(0)
	s_cmp_gt_u32 s61, 4
	s_cselect_b64 exec, -1, 0
	v_pk_add_f32 v[64:65], v[64:65], v[96:97]
	v_pk_add_f32 v[66:67], v[66:67], v[98:99]
	v_pk_add_f32 v[68:69], v[68:69], v[100:101]
	v_pk_add_f32 v[70:71], v[70:71], v[102:103]
	s_mov_b64 exec, -1
	ds_read_b128 v[72:75], v106 offset:10240
	ds_read_b128 v[76:79], v106 offset:10256
	ds_read_b128 v[80:83], v107 offset:10240
	ds_read_b128 v[84:87], v107 offset:10256
	ds_read_b128 v[88:91], v108 offset:10240
	ds_read_b128 v[92:95], v108 offset:10256
	ds_read_b128 v[96:99], v109 offset:10240
	ds_read_b128 v[100:103], v109 offset:10256
	s_waitcnt lgkmcnt(6)
	s_cmp_gt_u32 s58, 5
	s_cselect_b64 exec, -1, 0
	v_pk_add_f32 v[40:41], v[40:41], v[72:73]
	v_pk_add_f32 v[42:43], v[42:43], v[74:75]
	v_pk_add_f32 v[44:45], v[44:45], v[76:77]
	v_pk_add_f32 v[46:47], v[46:47], v[78:79]
	s_waitcnt lgkmcnt(4)
	s_cmp_gt_u32 s59, 5
	s_cselect_b64 exec, -1, 0
	v_pk_add_f32 v[48:49], v[48:49], v[80:81]
	v_pk_add_f32 v[50:51], v[50:51], v[82:83]
	v_pk_add_f32 v[52:53], v[52:53], v[84:85]
	v_pk_add_f32 v[54:55], v[54:55], v[86:87]
	s_waitcnt lgkmcnt(2)
	s_cmp_gt_u32 s60, 5
	s_cselect_b64 exec, -1, 0
	v_pk_add_f32 v[56:57], v[56:57], v[88:89]
	v_pk_add_f32 v[58:59], v[58:59], v[90:91]
	v_pk_add_f32 v[60:61], v[60:61], v[92:93]
	v_pk_add_f32 v[62:63], v[62:63], v[94:95]
	s_waitcnt lgkmcnt(0)
	s_cmp_gt_u32 s61, 5
	s_cselect_b64 exec, -1, 0
	v_pk_add_f32 v[64:65], v[64:65], v[96:97]
	v_pk_add_f32 v[66:67], v[66:67], v[98:99]
	v_pk_add_f32 v[68:69], v[68:69], v[100:101]
	v_pk_add_f32 v[70:71], v[70:71], v[102:103]
	s_mov_b64 exec, -1
	ds_read_b128 v[72:75], v106 offset:12288
	ds_read_b128 v[76:79], v106 offset:12304
	ds_read_b128 v[80:83], v107 offset:12288
	ds_read_b128 v[84:87], v107 offset:12304
	ds_read_b128 v[88:91], v108 offset:12288
	ds_read_b128 v[92:95], v108 offset:12304
	ds_read_b128 v[96:99], v109 offset:12288
	ds_read_b128 v[100:103], v109 offset:12304
	s_waitcnt lgkmcnt(6)
	s_cmp_gt_u32 s58, 6
	s_cselect_b64 exec, -1, 0
	v_pk_add_f32 v[40:41], v[40:41], v[72:73]
	v_pk_add_f32 v[42:43], v[42:43], v[74:75]
	v_pk_add_f32 v[44:45], v[44:45], v[76:77]
	v_pk_add_f32 v[46:47], v[46:47], v[78:79]
	s_waitcnt lgkmcnt(4)
	s_cmp_gt_u32 s59, 6
	s_cselect_b64 exec, -1, 0
	v_pk_add_f32 v[48:49], v[48:49], v[80:81]
	v_pk_add_f32 v[50:51], v[50:51], v[82:83]
	v_pk_add_f32 v[52:53], v[52:53], v[84:85]
	v_pk_add_f32 v[54:55], v[54:55], v[86:87]
	s_waitcnt lgkmcnt(2)
	s_cmp_gt_u32 s60, 6
	s_cselect_b64 exec, -1, 0
	v_pk_add_f32 v[56:57], v[56:57], v[88:89]
	v_pk_add_f32 v[58:59], v[58:59], v[90:91]
	v_pk_add_f32 v[60:61], v[60:61], v[92:93]
	v_pk_add_f32 v[62:63], v[62:63], v[94:95]
	s_waitcnt lgkmcnt(0)
	s_cmp_gt_u32 s61, 6
	s_cselect_b64 exec, -1, 0
	v_pk_add_f32 v[64:65], v[64:65], v[96:97]
	v_pk_add_f32 v[66:67], v[66:67], v[98:99]
	v_pk_add_f32 v[68:69], v[68:69], v[100:101]
	v_pk_add_f32 v[70:71], v[70:71], v[102:103]
	s_mov_b64 exec, -1
	ds_read_b128 v[72:75], v106 offset:14336
	ds_read_b128 v[76:79], v106 offset:14352
	ds_read_b128 v[80:83], v107 offset:14336
	ds_read_b128 v[84:87], v107 offset:14352
	ds_read_b128 v[88:91], v108 offset:14336
	ds_read_b128 v[92:95], v108 offset:14352
	ds_read_b128 v[96:99], v109 offset:14336
	ds_read_b128 v[100:103], v109 offset:14352
	s_waitcnt lgkmcnt(6)
	s_cmp_gt_u32 s58, 7
	s_cselect_b64 exec, -1, 0
	v_pk_add_f32 v[40:41], v[40:41], v[72:73]
	v_pk_add_f32 v[42:43], v[42:43], v[74:75]
	v_pk_add_f32 v[44:45], v[44:45], v[76:77]
	v_pk_add_f32 v[46:47], v[46:47], v[78:79]
	s_waitcnt lgkmcnt(4)
	s_cmp_gt_u32 s59, 7
	s_cselect_b64 exec, -1, 0
	v_pk_add_f32 v[48:49], v[48:49], v[80:81]
	v_pk_add_f32 v[50:51], v[50:51], v[82:83]
	v_pk_add_f32 v[52:53], v[52:53], v[84:85]
	v_pk_add_f32 v[54:55], v[54:55], v[86:87]
	s_waitcnt lgkmcnt(2)
	s_cmp_gt_u32 s60, 7
	s_cselect_b64 exec, -1, 0
	v_pk_add_f32 v[56:57], v[56:57], v[88:89]
	v_pk_add_f32 v[58:59], v[58:59], v[90:91]
	v_pk_add_f32 v[60:61], v[60:61], v[92:93]
	v_pk_add_f32 v[62:63], v[62:63], v[94:95]
	s_waitcnt lgkmcnt(0)
	s_cmp_gt_u32 s61, 7
	s_cselect_b64 exec, -1, 0
	v_pk_add_f32 v[64:65], v[64:65], v[96:97]
	v_pk_add_f32 v[66:67], v[66:67], v[98:99]
	v_pk_add_f32 v[68:69], v[68:69], v[100:101]
	v_pk_add_f32 v[70:71], v[70:71], v[102:103]
	s_mov_b64 exec, -1
	s_cmp_le_u32 s11, 8
	s_cbranch_scc1 .Lbox_p1_done
; #define LAS __attribute__((address_space(3)))
; __device__ void boxfilter_unit(const Params& p, LAS unsigned char* lds, int u) {
;     ...
;     for (int i = 0; i < 4; ++i) { const int tok = tid + 512 * i; const int r = tok >> 6, c = tok & 63; const int lo = max(r - hw, 0), hi = min(r + hw, 32);
;         f32x4 s0 = (f32x4){0.f, 0.f, 0.f, 0.f}, s1 = s0;
;         for (int rr = lo; rr < hi; ++rr) { s0 += *(const LAS f32x4*)(X + (rr * 64 + c) * 8); s1 += *(const LAS f32x4*)(X + (rr * 64 + c) * 8 + 4); }
;         const float cnt = (float)(hi - lo);
;         *(LAS f32x4*)(Y + tok * 8) = s0 / cnt; *(LAS f32x4*)(Y + tok * 8 + 4) = s1 / cnt; }
	ds_read_b128 v[72:75], v106 offset:16384
	ds_read_b128 v[76:79], v106 offset:16400
	ds_read_b128 v[80:83], v107 offset:16384
	ds_read_b128 v[84:87], v107 offset:16400
	ds_read_b128 v[88:91], v108 offset:16384
	ds_read_b128 v[92:95], v108 offset:16400
	ds_read_b128 v[96:99], v109 offset:16384
	ds_read_b128 v[100:103], v109 offset:16400
	s_waitcnt lgkmcnt(6)
	s_cmp_gt_u32 s58, 8
	s_cselect_b64 exec, -1, 0
	v_pk_add_f32 v[40:41], v[40:41], v[72:73]
	v_pk_add_f32 v[42:43], v[42:43], v[74:75]
	v_pk_add_f32 v[44:45], v[44:45], v[76:77]
	v_pk_add_f32 v[46:47], v[46:47], v[78:79]
	s_waitcnt lgkmcnt(4)
	s_cmp_gt_u32 s59, 8
	s_cselect_b64 exec, -1, 0
	v_pk_add_f32 v[48:49], v[48:49], v[80:81]
	v_pk_add_f32 v[50:51], v[50:51], v[82:83]
	v_pk_add_f32 v[52:53], v[52:53], v[84:85]
	v_pk_add_f32 v[54:55], v[54:55], v[86:87]
	s_waitcnt lgkmcnt(2)
	s_cmp_gt_u32 s60, 8
	s_cselect_b64 exec, -1, 0
	v_pk_add_f32 v[56:57], v[56:57], v[88:89]
	v_pk_add_f32 v[58:59], v[58:59], v[90:91]
	v_pk_add_f32 v[60:61], v[60:61], v[92:93]
	v_pk_add_f32 v[62:63], v[62:63], v[94:95]
	s_waitcnt lgkmcnt(0)
	s_cmp_gt_u32 s61, 8
	s_cselect_b64 exec, -1, 0
	v_pk_add_f32 v[64:65], v[64:65], v[96:97]
	v_pk_add_f32 v[66:67], v[66:67], v[98:99]
	v_pk_add_f32 v[68:69], v[68:69], v[100:101]
	v_pk_add_f32 v[70:71], v[70:71], v[102:103]
	s_mov_b64 exec, -1
	ds_read_b128 v[72:75], v106 offset:18432
	ds_read_b128 v[76:79], v106 offset:18448
	ds_read_b128 v[80:83], v107 offset:18432
	ds_read_b128 v[84:87], v107 offset:18448
	ds_read_b128 v[88:91], v108 offset:18432
	ds_read_b128 v[92:95], v108 offset:18448
	ds_read_b128 v[96:99], v109 offset:18432
	ds_read_b128 v[100:103], v109 offset:18448
	s_waitcnt lgkmcnt(6)
	s_cmp_gt_u32 s58, 9
	s_cselect_b64 exec, -1, 0
	v_pk_add_f32 v[40:41], v[40:41], v[72:73]
	v_pk_add_f32 v[42:43], v[42:43], v[74:75]
	v_pk_add_f32 v[44:45], v[44:45], v[76:77]
	v_pk_add_f32 v[46:47], v[46:47], v[78:79]
	s_waitcnt lgkmcnt(4)
	s_cmp_gt_u32 s59, 9
	s_cselect_b64 exec, -1, 0
	v_pk_add_f32 v[48:49], v[48:49], v[80:81]
	v_pk_add_f32 v[50:51], v[50:51], v[82:83]
	v_pk_add_f32 v[52:53], v[52:53], v[84:85]
	v_pk_add_f32 v[54:55], v[54:55], v[86:87]
	s_waitcnt lgkmcnt(2)
	s_cmp_gt_u32 s60, 9
	s_cselect_b64 exec, -1, 0
	v_pk_add_f32 v[56:57], v[56:57], v[88:89]
	v_pk_add_f32 v[58:59], v[58:59], v[90:91]
	v_pk_add_f32 v[60:61], v[60:61], v[92:93]
	v_pk_add_f32 v[62:63], v[62:63], v[94:95]
	s_waitcnt lgkmcnt(0)
	s_cmp_gt_u32 s61, 9
	s_cselect_b64 exec, -1, 0
	v_pk_add_f32 v[64:65], v[64:65], v[96:97]
	v_pk_add_f32 v[66:67], v[66:67], v[98:99]
	v_pk_add_f32 v[68:69], v[68:69], v[100:101]
	v_pk_add_f32 v[70:71], v[70:71], v[102:103]
	s_mov_b64 exec, -1
	ds_read_b128 v[72:75], v106 offset:20480
	ds_read_b128 v[76:79], v106 offset:20496
	ds_read_b128 v[80:83], v107 offset:20480
	ds_read_b128 v[84:87], v107 offset:20496
	ds_read_b128 v[88:91], v108 offset:20480
	ds_read_b128 v[92:95], v108 offset:20496
	ds_read_b128 v[96:99], v109 offset:20480
	ds_read_b128 v[100:103], v109 offset:20496
	s_waitcnt lgkmcnt(6)
	s_cmp_gt_u32 s58, 10
	s_cselect_b64 exec, -1, 0
	v_pk_add_f32 v[40:41], v[40:41], v[72:73]
	v_pk_add_f32 v[42:43], v[42:43], v[74:75]
	v_pk_add_f32 v[44:45], v[44:45], v[76:77]
	v_pk_add_f32 v[46:47], v[46:47], v[78:79]
	s_waitcnt lgkmcnt(4)
	s_cmp_gt_u32 s59, 10
	s_cselect_b64 exec, -1, 0
	v_pk_add_f32 v[48:49], v[48:49], v[80:81]
	v_pk_add_f32 v[50:51], v[50:51], v[82:83]
	v_pk_add_f32 v[52:53], v[52:53], v[84:85]
	v_pk_add_f32 v[54:55], v[54:55], v[86:87]
	s_waitcnt lgkmcnt(2)
	s_cmp_gt_u32 s60, 10
	s_cselect_b64 exec, -1, 0
	v_pk_add_f32 v[56:57], v[56:57], v[88:89]
	v_pk_add_f32 v[58:59], v[58:59], v[90:91]
	v_pk_add_f32 v[60:61], v[60:61], v[92:93]
	v_pk_add_f32 v[62:63], v[62:63], v[94:95]
	s_waitcnt lgkmcnt(0)
	s_cmp_gt_u32 s61, 10
	s_cselect_b64 exec, -1, 0
	v_pk_add_f32 v[64:65], v[64:65], v[96:97]
	v_pk_add_f32 v[66:67], v[66:67], v[98:99]
	v_pk_add_f32 v[68:69], v[68:69], v[100:101]
	v_pk_add_f32 v[70:71], v[70:71], v[102:103]
	s_mov_b64 exec, -1
	ds_read_b128 v[72:75], v106 offset:22528
	ds_read_b128 v[76:79], v106 offset:22544
	ds_read_b128 v[80:83], v107 offset:22528
	ds_read_b128 v[84:87], v107 offset:22544
	ds_read_b128 v[88:91], v108 offset:22528
	ds_read_b128 v[92:95], v108 offset:22544
	ds_read_b128 v[96:99], v109 offset:22528
	ds_read_b128 v[100:103], v109 offset:22544
	s_waitcnt lgkmcnt(6)
	s_cmp_gt_u32 s58, 11
	s_cselect_b64 exec, -1, 0
	v_pk_add_f32 v[40:41], v[40:41], v[72:73]
	v_pk_add_f32 v[42:43], v[42:43], v[74:75]
	v_pk_add_f32 v[44:45], v[44:45], v[76:77]
	v_pk_add_f32 v[46:47], v[46:47], v[78:79]
	s_waitcnt lgkmcnt(4)
	s_cmp_gt_u32 s59, 11
	s_cselect_b64 exec, -1, 0
	v_pk_add_f32 v[48:49], v[48:49], v[80:81]
	v_pk_add_f32 v[50:51], v[50:51], v[82:83]
	v_pk_add_f32 v[52:53], v[52:53], v[84:85]
	v_pk_add_f32 v[54:55], v[54:55], v[86:87]
	s_waitcnt lgkmcnt(2)
	s_cmp_gt_u32 s60, 11
	s_cselect_b64 exec, -1, 0
	v_pk_add_f32 v[56:57], v[56:57], v[88:89]
	v_pk_add_f32 v[58:59], v[58:59], v[90:91]
	v_pk_add_f32 v[60:61], v[60:61], v[92:93]
	v_pk_add_f32 v[62:63], v[62:63], v[94:95]
	s_waitcnt lgkmcnt(0)
	s_cmp_gt_u32 s61, 11
	s_cselect_b64 exec, -1, 0
	v_pk_add_f32 v[64:65], v[64:65], v[96:97]
	v_pk_add_f32 v[66:67], v[66:67], v[98:99]
	v_pk_add_f32 v[68:69], v[68:69], v[100:101]
	v_pk_add_f32 v[70:71], v[70:71], v[102:103]
	s_mov_b64 exec, -1
	ds_read_b128 v[72:75], v106 offset:24576
	ds_read_b128 v[76:79], v106 offset:24592
	ds_read_b128 v[80:83], v107 offset:24576
	ds_read_b128 v[84:87], v107 offset:24592
	ds_read_b128 v[88:91], v108 offset:24576
	ds_read_b128 v[92:95], v108 offset:24592
	ds_read_b128 v[96:99], v109 offset:24576
	ds_read_b128 v[100:103], v109 offset:24592
	s_waitcnt lgkmcnt(6)
; #define LAS __attribute__((address_space(3)))
; __device__ void boxfilter_unit(const Params& p, LAS unsigned char* lds, int u) {
;     ...
;     for (int i = 0; i < 4; ++i) { const int tok = tid + 512 * i; const int r = tok >> 6, c = tok & 63; const int lo = max(r - hw, 0), hi = min(r + hw, 32);
;         f32x4 s0 = (f32x4){0.f, 0.f, 0.f, 0.f}, s1 = s0;
;         for (int rr = lo; rr < hi; ++rr) { s0 += *(const LAS f32x4*)(X + (rr * 64 + c) * 8); s1 += *(const LAS f32x4*)(X + (rr * 64 + c) * 8 + 4); }
;         const float cnt = (float)(hi - lo);
;         *(LAS f32x4*)(Y + tok * 8) = s0 / cnt; *(LAS f32x4*)(Y + tok * 8 + 4) = s1 / cnt; }
	s_cmp_gt_u32 s58, 12
	s_cselect_b64 exec, -1, 0
	v_pk_add_f32 v[40:41], v[40:41], v[72:73]
	v_pk_add_f32 v[42:43], v[42:43], v[74:75]
	v_pk_add_f32 v[44:45], v[44:45], v[76:77]
	v_pk_add_f32 v[46:47], v[46:47], v[78:79]
	s_waitcnt lgkmcnt(4)
	s_cmp_gt_u32 s59, 12
	s_cselect_b64 exec, -1, 0
	v_pk_add_f32 v[48:49], v[48:49], v[80:81]
	v_pk_add_f32 v[50:51], v[50:51], v[82:83]
	v_pk_add_f32 v[52:53], v[52:53], v[84:85]
	v_pk_add_f32 v[54:55], v[54:55], v[86:87]
	s_waitcnt lgkmcnt(2)
	s_cmp_gt_u32 s60, 12
	s_cselect_b64 exec, -1, 0
	v_pk_add_f32 v[56:57], v[56:57], v[88:89]
	v_pk_add_f32 v[58:59], v[58:59], v[90:91]
	v_pk_add_f32 v[60:61], v[60:61], v[92:93]
	v_pk_add_f32 v[62:63], v[62:63], v[94:95]
	s_waitcnt lgkmcnt(0)
	s_cmp_gt_u32 s61, 12
	s_cselect_b64 exec, -1, 0
	v_pk_add_f32 v[64:65], v[64:65], v[96:97]
	v_pk_add_f32 v[66:67], v[66:67], v[98:99]
	v_pk_add_f32 v[68:69], v[68:69], v[100:101]
	v_pk_add_f32 v[70:71], v[70:71], v[102:103]
	s_mov_b64 exec, -1
	ds_read_b128 v[72:75], v106 offset:26624
	ds_read_b128 v[76:79], v106 offset:26640
	ds_read_b128 v[80:83], v107 offset:26624
	ds_read_b128 v[84:87], v107 offset:26640
	ds_read_b128 v[88:91], v108 offset:26624
	ds_read_b128 v[92:95], v108 offset:26640
	ds_read_b128 v[96:99], v109 offset:26624
	ds_read_b128 v[100:103], v109 offset:26640
	s_waitcnt lgkmcnt(6)
	s_cmp_gt_u32 s58, 13
	s_cselect_b64 exec, -1, 0
	v_pk_add_f32 v[40:41], v[40:41], v[72:73]
	v_pk_add_f32 v[42:43], v[42:43], v[74:75]
	v_pk_add_f32 v[44:45], v[44:45], v[76:77]
	v_pk_add_f32 v[46:47], v[46:47], v[78:79]
	s_waitcnt lgkmcnt(4)
	s_cmp_gt_u32 s59, 13
	s_cselect_b64 exec, -1, 0
	v_pk_add_f32 v[48:49], v[48:49], v[80:81]
	v_pk_add_f32 v[50:51], v[50:51], v[82:83]
	v_pk_add_f32 v[52:53], v[52:53], v[84:85]
	v_pk_add_f32 v[54:55], v[54:55], v[86:87]
	s_waitcnt lgkmcnt(2)
	s_cmp_gt_u32 s60, 13
	s_cselect_b64 exec, -1, 0
	v_pk_add_f32 v[56:57], v[56:57], v[88:89]
	v_pk_add_f32 v[58:59], v[58:59], v[90:91]
	v_pk_add_f32 v[60:61], v[60:61], v[92:93]
	v_pk_add_f32 v[62:63], v[62:63], v[94:95]
	s_waitcnt lgkmcnt(0)
	s_cmp_gt_u32 s61, 13
	s_cselect_b64 exec, -1, 0
	v_pk_add_f32 v[64:65], v[64:65], v[96:97]
	v_pk_add_f32 v[66:67], v[66:67], v[98:99]
	v_pk_add_f32 v[68:69], v[68:69], v[100:101]
	v_pk_add_f32 v[70:71], v[70:71], v[102:103]
	s_mov_b64 exec, -1
	ds_read_b128 v[72:75], v106 offset:28672
	ds_read_b128 v[76:79], v106 offset:28688
	ds_read_b128 v[80:83], v107 offset:28672
	ds_read_b128 v[84:87], v107 offset:28688
	ds_read_b128 v[88:91], v108 offset:28672
	ds_read_b128 v[92:95], v108 offset:28688
	ds_read_b128 v[96:99], v109 offset:28672
	ds_read_b128 v[100:103], v109 offset:28688
	s_waitcnt lgkmcnt(6)
	s_cmp_gt_u32 s58, 14
	s_cselect_b64 exec, -1, 0
	v_pk_add_f32 v[40:41], v[40:41], v[72:73]
	v_pk_add_f32 v[42:43], v[42:43], v[74:75]
	v_pk_add_f32 v[44:45], v[44:45], v[76:77]
	v_pk_add_f32 v[46:47], v[46:47], v[78:79]
	s_waitcnt lgkmcnt(4)
	s_cmp_gt_u32 s59, 14
	s_cselect_b64 exec, -1, 0
	v_pk_add_f32 v[48:49], v[48:49], v[80:81]
	v_pk_add_f32 v[50:51], v[50:51], v[82:83]
	v_pk_add_f32 v[52:53], v[52:53], v[84:85]
	v_pk_add_f32 v[54:55], v[54:55], v[86:87]
	s_waitcnt lgkmcnt(2)
	s_cmp_gt_u32 s60, 14
	s_cselect_b64 exec, -1, 0
	v_pk_add_f32 v[56:57], v[56:57], v[88:89]
	v_pk_add_f32 v[58:59], v[58:59], v[90:91]
	v_pk_add_f32 v[60:61], v[60:61], v[92:93]
	v_pk_add_f32 v[62:63], v[62:63], v[94:95]
	s_waitcnt lgkmcnt(0)
	s_cmp_gt_u32 s61, 14
	s_cselect_b64 exec, -1, 0
	v_pk_add_f32 v[64:65], v[64:65], v[96:97]
	v_pk_add_f32 v[66:67], v[66:67], v[98:99]
	v_pk_add_f32 v[68:69], v[68:69], v[100:101]
	v_pk_add_f32 v[70:71], v[70:71], v[102:103]
	s_mov_b64 exec, -1
	ds_read_b128 v[72:75], v106 offset:30720
	ds_read_b128 v[76:79], v106 offset:30736
	ds_read_b128 v[80:83], v107 offset:30720
	ds_read_b128 v[84:87], v107 offset:30736
	ds_read_b128 v[88:91], v108 offset:30720
	ds_read_b128 v[92:95], v108 offset:30736
	ds_read_b128 v[96:99], v109 offset:30720
	ds_read_b128 v[100:103], v109 offset:30736
	s_waitcnt lgkmcnt(6)
	s_cmp_gt_u32 s58, 15
	s_cselect_b64 exec, -1, 0
	v_pk_add_f32 v[40:41], v[40:41], v[72:73]
	v_pk_add_f32 v[42:43], v[42:43], v[74:75]
	v_pk_add_f32 v[44:45], v[44:45], v[76:77]
	v_pk_add_f32 v[46:47], v[46:47], v[78:79]
	s_waitcnt lgkmcnt(4)
	s_cmp_gt_u32 s59, 15
	s_cselect_b64 exec, -1, 0
	v_pk_add_f32 v[48:49], v[48:49], v[80:81]
	v_pk_add_f32 v[50:51], v[50:51], v[82:83]
	v_pk_add_f32 v[52:53], v[52:53], v[84:85]
	v_pk_add_f32 v[54:55], v[54:55], v[86:87]
	s_waitcnt lgkmcnt(2)
	s_cmp_gt_u32 s60, 15
	s_cselect_b64 exec, -1, 0
	v_pk_add_f32 v[56:57], v[56:57], v[88:89]
	v_pk_add_f32 v[58:59], v[58:59], v[90:91]
	v_pk_add_f32 v[60:61], v[60:61], v[92:93]
	v_pk_add_f32 v[62:63], v[62:63], v[94:95]
	s_waitcnt lgkmcnt(0)
	s_cmp_gt_u32 s61, 15
	s_cselect_b64 exec, -1, 0
	v_pk_add_f32 v[64:65], v[64:65], v[96:97]
	v_pk_add_f32 v[66:67], v[66:67], v[98:99]
	v_pk_add_f32 v[68:69], v[68:69], v[100:101]
	v_pk_add_f32 v[70:71], v[70:71], v[102:103]
	s_mov_b64 exec, -1
; #define LAS __attribute__((address_space(3)))
; __device__ void boxfilter_unit(const Params& p, LAS unsigned char* lds, int u) {
;     ...
;     for (int i = 0; i < 4; ++i) { const int tok = tid + 512 * i; const int r = tok >> 6, c = tok & 63; const int lo = max(r - hw, 0), hi = min(r + hw, 32);
;         f32x4 s0 = (f32x4){0.f, 0.f, 0.f, 0.f}, s1 = s0;
;         for (int rr = lo; rr < hi; ++rr) { s0 += *(const LAS f32x4*)(X + (rr * 64 + c) * 8); s1 += *(const LAS f32x4*)(X + (rr * 64 + c) * 8 + 4); }
;         const float cnt = (float)(hi - lo);
;         *(LAS f32x4*)(Y + tok * 8) = s0 / cnt; *(LAS f32x4*)(Y + tok * 8 + 4) = s1 / cnt; }
;     __syncthreads();
;     for (int i = 0; i < 4; ++i) { const int tok = tid + 512 * i; const int r = tok >> 6, c = tok & 63; const int lo = max(c - hw, 0), hi = min(c + hw, 64);
;         f32x4 s0 = (f32x4){0.f, 0.f, 0.f, 0.f}, s1 = s0;
.Lbox_p1_done:
	s_mov_b64 exec, -1
	v_cvt_f32_i32_e32 v112, s58
	v_rcp_f32_e32 v113, v112
	s_nop 0
	v_fma_f32 v114, -v112, v113, 1.0
	v_fmac_f32_e32 v113, v114, v113
	v_fma_f32 v114, -v112, v113, 1.0
	v_fmac_f32_e32 v113, v114, v113
	v_mul_f32_e32 v115, v40, v113
	v_fma_f32 v116, -v112, v115, v40
	v_fma_f32 v40, v116, v113, v115
	v_mul_f32_e32 v115, v41, v113
	v_fma_f32 v116, -v112, v115, v41
	v_fma_f32 v41, v116, v113, v115
	v_mul_f32_e32 v115, v42, v113
	v_fma_f32 v116, -v112, v115, v42
	v_fma_f32 v42, v116, v113, v115
	v_mul_f32_e32 v115, v43, v113
	v_fma_f32 v116, -v112, v115, v43
	v_fma_f32 v43, v116, v113, v115
	v_mul_f32_e32 v115, v44, v113
	v_fma_f32 v116, -v112, v115, v44
	v_fma_f32 v44, v116, v113, v115
	v_mul_f32_e32 v115, v45, v113
	v_fma_f32 v116, -v112, v115, v45
	v_fma_f32 v45, v116, v113, v115
	v_mul_f32_e32 v115, v46, v113
	v_fma_f32 v116, -v112, v115, v46
	v_fma_f32 v46, v116, v113, v115
	v_mul_f32_e32 v115, v47, v113
	v_fma_f32 v116, -v112, v115, v47
	v_fma_f32 v47, v116, v113, v115
	v_cvt_f32_i32_e32 v112, s59
	v_rcp_f32_e32 v113, v112
	s_nop 0
	v_fma_f32 v114, -v112, v113, 1.0
	v_fmac_f32_e32 v113, v114, v113
	v_fma_f32 v114, -v112, v113, 1.0
	v_fmac_f32_e32 v113, v114, v113
	v_mul_f32_e32 v115, v48, v113
	v_fma_f32 v116, -v112, v115, v48
	v_fma_f32 v48, v116, v113, v115
	v_mul_f32_e32 v115, v49, v113
	v_fma_f32 v116, -v112, v115, v49
	v_fma_f32 v49, v116, v113, v115
	v_mul_f32_e32 v115, v50, v113
	v_fma_f32 v116, -v112, v115, v50
	v_fma_f32 v50, v116, v113, v115
	v_mul_f32_e32 v115, v51, v113
	v_fma_f32 v116, -v112, v115, v51
	v_fma_f32 v51, v116, v113, v115
	v_mul_f32_e32 v115, v52, v113
	v_fma_f32 v116, -v112, v115, v52
	v_fma_f32 v52, v116, v113, v115
	v_mul_f32_e32 v115, v53, v113
	v_fma_f32 v116, -v112, v115, v53
	v_fma_f32 v53, v116, v113, v115
	v_mul_f32_e32 v115, v54, v113
	v_fma_f32 v116, -v112, v115, v54
	v_fma_f32 v54, v116, v113, v115
	v_mul_f32_e32 v115, v55, v113
	v_fma_f32 v116, -v112, v115, v55
	v_fma_f32 v55, v116, v113, v115
	v_cvt_f32_i32_e32 v112, s60
	v_rcp_f32_e32 v113, v112
	s_nop 0
	v_fma_f32 v114, -v112, v113, 1.0
	v_fmac_f32_e32 v113, v114, v113
	v_fma_f32 v114, -v112, v113, 1.0
	v_fmac_f32_e32 v113, v114, v113
	v_mul_f32_e32 v115, v56, v113
	v_fma_f32 v116, -v112, v115, v56
	v_fma_f32 v56, v116, v113, v115
	v_mul_f32_e32 v115, v57, v113
	v_fma_f32 v116, -v112, v115, v57
	v_fma_f32 v57, v116, v113, v115
	v_mul_f32_e32 v115, v58, v113
	v_fma_f32 v116, -v112, v115, v58
	v_fma_f32 v58, v116, v113, v115
	v_mul_f32_e32 v115, v59, v113
	v_fma_f32 v116, -v112, v115, v59
	v_fma_f32 v59, v116, v113, v115
	v_mul_f32_e32 v115, v60, v113
	v_fma_f32 v116, -v112, v115, v60
	v_fma_f32 v60, v116, v113, v115
	v_mul_f32_e32 v115, v61, v113
	v_fma_f32 v116, -v112, v115, v61
	v_fma_f32 v61, v116, v113, v115
	v_mul_f32_e32 v115, v62, v113
	v_fma_f32 v116, -v112, v115, v62
	v_fma_f32 v62, v116, v113, v115
	v_mul_f32_e32 v115, v63, v113
	v_fma_f32 v116, -v112, v115, v63
	v_fma_f32 v63, v116, v113, v115
	v_cvt_f32_i32_e32 v112, s61
	v_rcp_f32_e32 v113, v112
	s_nop 0
	v_fma_f32 v114, -v112, v113, 1.0
	v_fmac_f32_e32 v113, v114, v113
	v_fma_f32 v114, -v112, v113, 1.0
	v_fmac_f32_e32 v113, v114, v113
	v_mul_f32_e32 v115, v64, v113
	v_fma_f32 v116, -v112, v115, v64
	v_fma_f32 v64, v116, v113, v115
	v_mul_f32_e32 v115, v65, v113
	v_fma_f32 v116, -v112, v115, v65
	v_fma_f32 v65, v116, v113, v115
	v_mul_f32_e32 v115, v66, v113
	v_fma_f32 v116, -v112, v115, v66
	v_fma_f32 v66, v116, v113, v115
	v_mul_f32_e32 v115, v67, v113
	v_fma_f32 v116, -v112, v115, v67
	v_fma_f32 v67, v116, v113, v115
	v_mul_f32_e32 v115, v68, v113
	v_fma_f32 v116, -v112, v115, v68
	v_fma_f32 v68, v116, v113, v115
	v_mul_f32_e32 v115, v69, v113
	v_fma_f32 v116, -v112, v115, v69
	v_fma_f32 v69, v116, v113, v115
	v_mul_f32_e32 v115, v70, v113
	v_fma_f32 v116, -v112, v115, v70
	v_fma_f32 v70, v116, v113, v115
	v_mul_f32_e32 v115, v71, v113
	v_fma_f32 v116, -v112, v115, v71
	v_fma_f32 v71, v116, v113, v115
	v_add_u32_e32 v9, 0x10000, v12
	ds_write_b128 v9, v[40:43]
	ds_write_b128 v9, v[44:47] offset:16
	ds_write_b128 v9, v[48:51] offset:16384
	ds_write_b128 v9, v[52:55] offset:16400
	ds_write_b128 v9, v[56:59] offset:32768
	ds_write_b128 v9, v[60:63] offset:32784
	ds_write_b128 v9, v[64:67] offset:49152
	ds_write_b128 v9, v[68:71] offset:49168
	v_subrev_u32_e32 v111, s10, v10
	v_max_i32_e32 v111, 0, v111
	v_add_u32_e32 v110, s10, v10
	v_min_i32_e32 v110, 64, v110
	v_sub_u32_e32 v110, v110, v111
	v_lshlrev_b32_e32 v111, 5, v111
	s_add_u32 s54, s6, 0
	s_lshl_b32 s54, s54, 11
	s_add_u32 s54, s54, 0x10000
	v_add_u32_e32 v106, s54, v111
	s_add_u32 s54, s6, 8
	s_lshl_b32 s54, s54, 11
	s_add_u32 s54, s54, 0x10000
	v_add_u32_e32 v107, s54, v111
	s_add_u32 s54, s6, 16
	s_lshl_b32 s54, s54, 11
	s_add_u32 s54, s54, 0x10000
	v_add_u32_e32 v108, s54, v111
	s_add_u32 s54, s6, 24
	s_lshl_b32 s54, s54, 11
	s_add_u32 s54, s54, 0x10000
	v_add_u32_e32 v109, s54, v111
	v_mov_b32_e32 v40, 0
	v_mov_b32_e32 v41, 0
	v_mov_b32_e32 v42, 0
	v_mov_b32_e32 v43, 0
	v_mov_b32_e32 v44, 0
	v_mov_b32_e32 v45, 0
	v_mov_b32_e32 v46, 0
	v_mov_b32_e32 v47, 0
	v_mov_b32_e32 v48, 0
	v_mov_b32_e32 v49, 0
	v_mov_b32_e32 v50, 0
	v_mov_b32_e32 v51, 0
	v_mov_b32_e32 v52, 0
	v_mov_b32_e32 v53, 0
	v_mov_b32_e32 v54, 0
	v_mov_b32_e32 v55, 0
	v_mov_b32_e32 v56, 0
	v_mov_b32_e32 v57, 0
	v_mov_b32_e32 v58, 0
	v_mov_b32_e32 v59, 0
	v_mov_b32_e32 v60, 0
	v_mov_b32_e32 v61, 0
	v_mov_b32_e32 v62, 0
	v_mov_b32_e32 v63, 0
	v_mov_b32_e32 v64, 0
	v_mov_b32_e32 v65, 0
	v_mov_b32_e32 v66, 0
	v_mov_b32_e32 v67, 0
	v_mov_b32_e32 v68, 0
	v_mov_b32_e32 v69, 0
	v_mov_b32_e32 v70, 0
	v_mov_b32_e32 v71, 0
	s_waitcnt lgkmcnt(0)
	s_barrier
; #define LAS __attribute__((address_space(3)))
; __device__ void boxfilter_unit(const Params& p, LAS unsigned char* lds, int u) {
;     ...
;     for (int i = 0; i < 4; ++i) { const int tok = tid + 512 * i; const int r = tok >> 6, c = tok & 63; const int lo = max(c - hw, 0), hi = min(c + hw, 64);
;         f32x4 s0 = (f32x4){0.f, 0.f, 0.f, 0.f}, s1 = s0;
;         for (int cc = lo; cc < hi; ++cc) { s0 += *(const LAS f32x4*)(Y + (r * 64 + cc) * 8); s1 += *(const LAS f32x4*)(Y + (r * 64 + cc) * 8 + 4); }
	s_mov_b64 exec, -1
	ds_read_b128 v[72:75], v106
	ds_read_b128 v[76:79], v106 offset:16
	ds_read_b128 v[80:83], v107
	ds_read_b128 v[84:87], v107 offset:16
	ds_read_b128 v[88:91], v108
	ds_read_b128 v[92:95], v108 offset:16
	ds_read_b128 v[96:99], v109
	ds_read_b128 v[100:103], v109 offset:16
	v_cmp_lt_u32_e32 vcc, 0, v110
	s_waitcnt lgkmcnt(6)
	s_mov_b64 exec, vcc
	v_pk_add_f32 v[40:41], v[40:41], v[72:73]
	v_pk_add_f32 v[42:43], v[42:43], v[74:75]
	v_pk_add_f32 v[44:45], v[44:45], v[76:77]
	v_pk_add_f32 v[46:47], v[46:47], v[78:79]
	s_waitcnt lgkmcnt(4)
	v_pk_add_f32 v[48:49], v[48:49], v[80:81]
	v_pk_add_f32 v[50:51], v[50:51], v[82:83]
	v_pk_add_f32 v[52:53], v[52:53], v[84:85]
	v_pk_add_f32 v[54:55], v[54:55], v[86:87]
	s_waitcnt lgkmcnt(2)
	v_pk_add_f32 v[56:57], v[56:57], v[88:89]
	v_pk_add_f32 v[58:59], v[58:59], v[90:91]
	v_pk_add_f32 v[60:61], v[60:61], v[92:93]
	v_pk_add_f32 v[62:63], v[62:63], v[94:95]
	s_waitcnt lgkmcnt(0)
	v_pk_add_f32 v[64:65], v[64:65], v[96:97]
	v_pk_add_f32 v[66:67], v[66:67], v[98:99]
	v_pk_add_f32 v[68:69], v[68:69], v[100:101]
	v_pk_add_f32 v[70:71], v[70:71], v[102:103]
	s_mov_b64 exec, -1
	ds_read_b128 v[72:75], v106 offset:32
	ds_read_b128 v[76:79], v106 offset:48
	ds_read_b128 v[80:83], v107 offset:32
	ds_read_b128 v[84:87], v107 offset:48
	ds_read_b128 v[88:91], v108 offset:32
	ds_read_b128 v[92:95], v108 offset:48
	ds_read_b128 v[96:99], v109 offset:32
	ds_read_b128 v[100:103], v109 offset:48
	v_cmp_lt_u32_e32 vcc, 1, v110
	s_waitcnt lgkmcnt(6)
	s_mov_b64 exec, vcc
	v_pk_add_f32 v[40:41], v[40:41], v[72:73]
	v_pk_add_f32 v[42:43], v[42:43], v[74:75]
	v_pk_add_f32 v[44:45], v[44:45], v[76:77]
	v_pk_add_f32 v[46:47], v[46:47], v[78:79]
	s_waitcnt lgkmcnt(4)
	v_pk_add_f32 v[48:49], v[48:49], v[80:81]
	v_pk_add_f32 v[50:51], v[50:51], v[82:83]
	v_pk_add_f32 v[52:53], v[52:53], v[84:85]
	v_pk_add_f32 v[54:55], v[54:55], v[86:87]
	s_waitcnt lgkmcnt(2)
	v_pk_add_f32 v[56:57], v[56:57], v[88:89]
	v_pk_add_f32 v[58:59], v[58:59], v[90:91]
	v_pk_add_f32 v[60:61], v[60:61], v[92:93]
	v_pk_add_f32 v[62:63], v[62:63], v[94:95]
	s_waitcnt lgkmcnt(0)
	v_pk_add_f32 v[64:65], v[64:65], v[96:97]
	v_pk_add_f32 v[66:67], v[66:67], v[98:99]
	v_pk_add_f32 v[68:69], v[68:69], v[100:101]
	v_pk_add_f32 v[70:71], v[70:71], v[102:103]
	s_cmp_le_u32 s11, 2
	s_cbranch_scc1 .Lbox_p2_done
	s_mov_b64 exec, -1
	ds_read_b128 v[72:75], v106 offset:64
	ds_read_b128 v[76:79], v106 offset:80
	ds_read_b128 v[80:83], v107 offset:64
	ds_read_b128 v[84:87], v107 offset:80
	ds_read_b128 v[88:91], v108 offset:64
	ds_read_b128 v[92:95], v108 offset:80
	ds_read_b128 v[96:99], v109 offset:64
	ds_read_b128 v[100:103], v109 offset:80
	v_cmp_lt_u32_e32 vcc, 2, v110
	s_waitcnt lgkmcnt(6)
	s_mov_b64 exec, vcc
	v_pk_add_f32 v[40:41], v[40:41], v[72:73]
	v_pk_add_f32 v[42:43], v[42:43], v[74:75]
	v_pk_add_f32 v[44:45], v[44:45], v[76:77]
	v_pk_add_f32 v[46:47], v[46:47], v[78:79]
	s_waitcnt lgkmcnt(4)
	v_pk_add_f32 v[48:49], v[48:49], v[80:81]
	v_pk_add_f32 v[50:51], v[50:51], v[82:83]
	v_pk_add_f32 v[52:53], v[52:53], v[84:85]
	v_pk_add_f32 v[54:55], v[54:55], v[86:87]
	s_waitcnt lgkmcnt(2)
	v_pk_add_f32 v[56:57], v[56:57], v[88:89]
	v_pk_add_f32 v[58:59], v[58:59], v[90:91]
	v_pk_add_f32 v[60:61], v[60:61], v[92:93]
	v_pk_add_f32 v[62:63], v[62:63], v[94:95]
	s_waitcnt lgkmcnt(0)
	v_pk_add_f32 v[64:65], v[64:65], v[96:97]
	v_pk_add_f32 v[66:67], v[66:67], v[98:99]
	v_pk_add_f32 v[68:69], v[68:69], v[100:101]
	v_pk_add_f32 v[70:71], v[70:71], v[102:103]
	s_mov_b64 exec, -1
	ds_read_b128 v[72:75], v106 offset:96
	ds_read_b128 v[76:79], v106 offset:112
	ds_read_b128 v[80:83], v107 offset:96
	ds_read_b128 v[84:87], v107 offset:112
	ds_read_b128 v[88:91], v108 offset:96
	ds_read_b128 v[92:95], v108 offset:112
	ds_read_b128 v[96:99], v109 offset:96
	ds_read_b128 v[100:103], v109 offset:112
	v_cmp_lt_u32_e32 vcc, 3, v110
	s_waitcnt lgkmcnt(6)
	s_mov_b64 exec, vcc
	v_pk_add_f32 v[40:41], v[40:41], v[72:73]
	v_pk_add_f32 v[42:43], v[42:43], v[74:75]
	v_pk_add_f32 v[44:45], v[44:45], v[76:77]
	v_pk_add_f32 v[46:47], v[46:47], v[78:79]
	s_waitcnt lgkmcnt(4)
	v_pk_add_f32 v[48:49], v[48:49], v[80:81]
	v_pk_add_f32 v[50:51], v[50:51], v[82:83]
	v_pk_add_f32 v[52:53], v[52:53], v[84:85]
	v_pk_add_f32 v[54:55], v[54:55], v[86:87]
	s_waitcnt lgkmcnt(2)
	v_pk_add_f32 v[56:57], v[56:57], v[88:89]
	v_pk_add_f32 v[58:59], v[58:59], v[90:91]
	v_pk_add_f32 v[60:61], v[60:61], v[92:93]
	v_pk_add_f32 v[62:63], v[62:63], v[94:95]
	s_waitcnt lgkmcnt(0)
	v_pk_add_f32 v[64:65], v[64:65], v[96:97]
	v_pk_add_f32 v[66:67], v[66:67], v[98:99]
	v_pk_add_f32 v[68:69], v[68:69], v[100:101]
	v_pk_add_f32 v[70:71], v[70:71], v[102:103]
	s_cmp_le_u32 s11, 4
	s_cbranch_scc1 .Lbox_p2_done
; #define LAS __attribute__((address_space(3)))
; __device__ void boxfilter_unit(const Params& p, LAS unsigned char* lds, int u) {
;     ...
;     for (int i = 0; i < 4; ++i) { const int tok = tid + 512 * i; const int r = tok >> 6, c = tok & 63; const int lo = max(c - hw, 0), hi = min(c + hw, 64);
;         f32x4 s0 = (f32x4){0.f, 0.f, 0.f, 0.f}, s1 = s0;
;         for (int cc = lo; cc < hi; ++cc) { s0 += *(const LAS f32x4*)(Y + (r * 64 + cc) * 8); s1 += *(const LAS f32x4*)(Y + (r * 64 + cc) * 8 + 4); }
	s_mov_b64 exec, -1
	ds_read_b128 v[72:75], v106 offset:128
	ds_read_b128 v[76:79], v106 offset:144
	ds_read_b128 v[80:83], v107 offset:128
	ds_read_b128 v[84:87], v107 offset:144
	ds_read_b128 v[88:91], v108 offset:128
	ds_read_b128 v[92:95], v108 offset:144
	ds_read_b128 v[96:99], v109 offset:128
	ds_read_b128 v[100:103], v109 offset:144
	v_cmp_lt_u32_e32 vcc, 4, v110
	s_waitcnt lgkmcnt(6)
	s_mov_b64 exec, vcc
	v_pk_add_f32 v[40:41], v[40:41], v[72:73]
	v_pk_add_f32 v[42:43], v[42:43], v[74:75]
	v_pk_add_f32 v[44:45], v[44:45], v[76:77]
	v_pk_add_f32 v[46:47], v[46:47], v[78:79]
	s_waitcnt lgkmcnt(4)
	v_pk_add_f32 v[48:49], v[48:49], v[80:81]
	v_pk_add_f32 v[50:51], v[50:51], v[82:83]
	v_pk_add_f32 v[52:53], v[52:53], v[84:85]
	v_pk_add_f32 v[54:55], v[54:55], v[86:87]
	s_waitcnt lgkmcnt(2)
	v_pk_add_f32 v[56:57], v[56:57], v[88:89]
	v_pk_add_f32 v[58:59], v[58:59], v[90:91]
	v_pk_add_f32 v[60:61], v[60:61], v[92:93]
	v_pk_add_f32 v[62:63], v[62:63], v[94:95]
	s_waitcnt lgkmcnt(0)
	v_pk_add_f32 v[64:65], v[64:65], v[96:97]
	v_pk_add_f32 v[66:67], v[66:67], v[98:99]
	v_pk_add_f32 v[68:69], v[68:69], v[100:101]
	v_pk_add_f32 v[70:71], v[70:71], v[102:103]
	s_mov_b64 exec, -1
	ds_read_b128 v[72:75], v106 offset:160
	ds_read_b128 v[76:79], v106 offset:176
	ds_read_b128 v[80:83], v107 offset:160
	ds_read_b128 v[84:87], v107 offset:176
	ds_read_b128 v[88:91], v108 offset:160
	ds_read_b128 v[92:95], v108 offset:176
	ds_read_b128 v[96:99], v109 offset:160
	ds_read_b128 v[100:103], v109 offset:176
	v_cmp_lt_u32_e32 vcc, 5, v110
	s_waitcnt lgkmcnt(6)
	s_mov_b64 exec, vcc
	v_pk_add_f32 v[40:41], v[40:41], v[72:73]
	v_pk_add_f32 v[42:43], v[42:43], v[74:75]
	v_pk_add_f32 v[44:45], v[44:45], v[76:77]
	v_pk_add_f32 v[46:47], v[46:47], v[78:79]
	s_waitcnt lgkmcnt(4)
	v_pk_add_f32 v[48:49], v[48:49], v[80:81]
	v_pk_add_f32 v[50:51], v[50:51], v[82:83]
	v_pk_add_f32 v[52:53], v[52:53], v[84:85]
	v_pk_add_f32 v[54:55], v[54:55], v[86:87]
	s_waitcnt lgkmcnt(2)
	v_pk_add_f32 v[56:57], v[56:57], v[88:89]
	v_pk_add_f32 v[58:59], v[58:59], v[90:91]
	v_pk_add_f32 v[60:61], v[60:61], v[92:93]
	v_pk_add_f32 v[62:63], v[62:63], v[94:95]
	s_waitcnt lgkmcnt(0)
	v_pk_add_f32 v[64:65], v[64:65], v[96:97]
	v_pk_add_f32 v[66:67], v[66:67], v[98:99]
	v_pk_add_f32 v[68:69], v[68:69], v[100:101]
	v_pk_add_f32 v[70:71], v[70:71], v[102:103]
	s_mov_b64 exec, -1
	ds_read_b128 v[72:75], v106 offset:192
	ds_read_b128 v[76:79], v106 offset:208
	ds_read_b128 v[80:83], v107 offset:192
	ds_read_b128 v[84:87], v107 offset:208
	ds_read_b128 v[88:91], v108 offset:192
	ds_read_b128 v[92:95], v108 offset:208
	ds_read_b128 v[96:99], v109 offset:192
	ds_read_b128 v[100:103], v109 offset:208
	v_cmp_lt_u32_e32 vcc, 6, v110
	s_waitcnt lgkmcnt(6)
	s_mov_b64 exec, vcc
	v_pk_add_f32 v[40:41], v[40:41], v[72:73]
	v_pk_add_f32 v[42:43], v[42:43], v[74:75]
	v_pk_add_f32 v[44:45], v[44:45], v[76:77]
	v_pk_add_f32 v[46:47], v[46:47], v[78:79]
	s_waitcnt lgkmcnt(4)
	v_pk_add_f32 v[48:49], v[48:49], v[80:81]
	v_pk_add_f32 v[50:51], v[50:51], v[82:83]
	v_pk_add_f32 v[52:53], v[52:53], v[84:85]
	v_pk_add_f32 v[54:55], v[54:55], v[86:87]
	s_waitcnt lgkmcnt(2)
	v_pk_add_f32 v[56:57], v[56:57], v[88:89]
	v_pk_add_f32 v[58:59], v[58:59], v[90:91]
	v_pk_add_f32 v[60:61], v[60:61], v[92:93]
	v_pk_add_f32 v[62:63], v[62:63], v[94:95]
	s_waitcnt lgkmcnt(0)
	v_pk_add_f32 v[64:65], v[64:65], v[96:97]
	v_pk_add_f32 v[66:67], v[66:67], v[98:99]
	v_pk_add_f32 v[68:69], v[68:69], v[100:101]
	v_pk_add_f32 v[70:71], v[70:71], v[102:103]
	s_mov_b64 exec, -1
	ds_read_b128 v[72:75], v106 offset:224
	ds_read_b128 v[76:79], v106 offset:240
	ds_read_b128 v[80:83], v107 offset:224
	ds_read_b128 v[84:87], v107 offset:240
	ds_read_b128 v[88:91], v108 offset:224
	ds_read_b128 v[92:95], v108 offset:240
	ds_read_b128 v[96:99], v109 offset:224
	ds_read_b128 v[100:103], v109 offset:240
	v_cmp_lt_u32_e32 vcc, 7, v110
	s_waitcnt lgkmcnt(6)
	s_mov_b64 exec, vcc
	v_pk_add_f32 v[40:41], v[40:41], v[72:73]
	v_pk_add_f32 v[42:43], v[42:43], v[74:75]
	v_pk_add_f32 v[44:45], v[44:45], v[76:77]
	v_pk_add_f32 v[46:47], v[46:47], v[78:79]
	s_waitcnt lgkmcnt(4)
	v_pk_add_f32 v[48:49], v[48:49], v[80:81]
	v_pk_add_f32 v[50:51], v[50:51], v[82:83]
	v_pk_add_f32 v[52:53], v[52:53], v[84:85]
	v_pk_add_f32 v[54:55], v[54:55], v[86:87]
	s_waitcnt lgkmcnt(2)
	v_pk_add_f32 v[56:57], v[56:57], v[88:89]
	v_pk_add_f32 v[58:59], v[58:59], v[90:91]
	v_pk_add_f32 v[60:61], v[60:61], v[92:93]
	v_pk_add_f32 v[62:63], v[62:63], v[94:95]
	s_waitcnt lgkmcnt(0)
	v_pk_add_f32 v[64:65], v[64:65], v[96:97]
	v_pk_add_f32 v[66:67], v[66:67], v[98:99]
	v_pk_add_f32 v[68:69], v[68:69], v[100:101]
	v_pk_add_f32 v[70:71], v[70:71], v[102:103]
	s_cmp_le_u32 s11, 8
	s_cbranch_scc1 .Lbox_p2_done
; #define LAS __attribute__((address_space(3)))
; __device__ void boxfilter_unit(const Params& p, LAS unsigned char* lds, int u) {
;     ...
;     for (int i = 0; i < 4; ++i) { const int tok = tid + 512 * i; const int r = tok >> 6, c = tok & 63; const int lo = max(c - hw, 0), hi = min(c + hw, 64);
;         f32x4 s0 = (f32x4){0.f, 0.f, 0.f, 0.f}, s1 = s0;
;         for (int cc = lo; cc < hi; ++cc) { s0 += *(const LAS f32x4*)(Y + (r * 64 + cc) * 8); s1 += *(const LAS f32x4*)(Y + (r * 64 + cc) * 8 + 4); }
	s_mov_b64 exec, -1
	ds_read_b128 v[72:75], v106 offset:256
	ds_read_b128 v[76:79], v106 offset:272
	ds_read_b128 v[80:83], v107 offset:256
	ds_read_b128 v[84:87], v107 offset:272
	ds_read_b128 v[88:91], v108 offset:256
	ds_read_b128 v[92:95], v108 offset:272
	ds_read_b128 v[96:99], v109 offset:256
	ds_read_b128 v[100:103], v109 offset:272
	v_cmp_lt_u32_e32 vcc, 8, v110
	s_waitcnt lgkmcnt(6)
	s_mov_b64 exec, vcc
	v_pk_add_f32 v[40:41], v[40:41], v[72:73]
	v_pk_add_f32 v[42:43], v[42:43], v[74:75]
	v_pk_add_f32 v[44:45], v[44:45], v[76:77]
	v_pk_add_f32 v[46:47], v[46:47], v[78:79]
	s_waitcnt lgkmcnt(4)
	v_pk_add_f32 v[48:49], v[48:49], v[80:81]
	v_pk_add_f32 v[50:51], v[50:51], v[82:83]
	v_pk_add_f32 v[52:53], v[52:53], v[84:85]
	v_pk_add_f32 v[54:55], v[54:55], v[86:87]
	s_waitcnt lgkmcnt(2)
	v_pk_add_f32 v[56:57], v[56:57], v[88:89]
	v_pk_add_f32 v[58:59], v[58:59], v[90:91]
	v_pk_add_f32 v[60:61], v[60:61], v[92:93]
	v_pk_add_f32 v[62:63], v[62:63], v[94:95]
	s_waitcnt lgkmcnt(0)
	v_pk_add_f32 v[64:65], v[64:65], v[96:97]
	v_pk_add_f32 v[66:67], v[66:67], v[98:99]
	v_pk_add_f32 v[68:69], v[68:69], v[100:101]
	v_pk_add_f32 v[70:71], v[70:71], v[102:103]
	s_mov_b64 exec, -1
	ds_read_b128 v[72:75], v106 offset:288
	ds_read_b128 v[76:79], v106 offset:304
	ds_read_b128 v[80:83], v107 offset:288
	ds_read_b128 v[84:87], v107 offset:304
	ds_read_b128 v[88:91], v108 offset:288
	ds_read_b128 v[92:95], v108 offset:304
	ds_read_b128 v[96:99], v109 offset:288
	ds_read_b128 v[100:103], v109 offset:304
	v_cmp_lt_u32_e32 vcc, 9, v110
	s_waitcnt lgkmcnt(6)
	s_mov_b64 exec, vcc
	v_pk_add_f32 v[40:41], v[40:41], v[72:73]
	v_pk_add_f32 v[42:43], v[42:43], v[74:75]
	v_pk_add_f32 v[44:45], v[44:45], v[76:77]
	v_pk_add_f32 v[46:47], v[46:47], v[78:79]
	s_waitcnt lgkmcnt(4)
	v_pk_add_f32 v[48:49], v[48:49], v[80:81]
	v_pk_add_f32 v[50:51], v[50:51], v[82:83]
	v_pk_add_f32 v[52:53], v[52:53], v[84:85]
	v_pk_add_f32 v[54:55], v[54:55], v[86:87]
	s_waitcnt lgkmcnt(2)
	v_pk_add_f32 v[56:57], v[56:57], v[88:89]
	v_pk_add_f32 v[58:59], v[58:59], v[90:91]
	v_pk_add_f32 v[60:61], v[60:61], v[92:93]
	v_pk_add_f32 v[62:63], v[62:63], v[94:95]
	s_waitcnt lgkmcnt(0)
	v_pk_add_f32 v[64:65], v[64:65], v[96:97]
	v_pk_add_f32 v[66:67], v[66:67], v[98:99]
	v_pk_add_f32 v[68:69], v[68:69], v[100:101]
	v_pk_add_f32 v[70:71], v[70:71], v[102:103]
	s_mov_b64 exec, -1
	ds_read_b128 v[72:75], v106 offset:320
	ds_read_b128 v[76:79], v106 offset:336
	ds_read_b128 v[80:83], v107 offset:320
	ds_read_b128 v[84:87], v107 offset:336
	ds_read_b128 v[88:91], v108 offset:320
	ds_read_b128 v[92:95], v108 offset:336
	ds_read_b128 v[96:99], v109 offset:320
	ds_read_b128 v[100:103], v109 offset:336
	v_cmp_lt_u32_e32 vcc, 10, v110
	s_waitcnt lgkmcnt(6)
	s_mov_b64 exec, vcc
	v_pk_add_f32 v[40:41], v[40:41], v[72:73]
	v_pk_add_f32 v[42:43], v[42:43], v[74:75]
	v_pk_add_f32 v[44:45], v[44:45], v[76:77]
	v_pk_add_f32 v[46:47], v[46:47], v[78:79]
	s_waitcnt lgkmcnt(4)
	v_pk_add_f32 v[48:49], v[48:49], v[80:81]
	v_pk_add_f32 v[50:51], v[50:51], v[82:83]
	v_pk_add_f32 v[52:53], v[52:53], v[84:85]
	v_pk_add_f32 v[54:55], v[54:55], v[86:87]
	s_waitcnt lgkmcnt(2)
	v_pk_add_f32 v[56:57], v[56:57], v[88:89]
	v_pk_add_f32 v[58:59], v[58:59], v[90:91]
	v_pk_add_f32 v[60:61], v[60:61], v[92:93]
	v_pk_add_f32 v[62:63], v[62:63], v[94:95]
	s_waitcnt lgkmcnt(0)
	v_pk_add_f32 v[64:65], v[64:65], v[96:97]
	v_pk_add_f32 v[66:67], v[66:67], v[98:99]
	v_pk_add_f32 v[68:69], v[68:69], v[100:101]
	v_pk_add_f32 v[70:71], v[70:71], v[102:103]
	s_mov_b64 exec, -1
	ds_read_b128 v[72:75], v106 offset:352
	ds_read_b128 v[76:79], v106 offset:368
	ds_read_b128 v[80:83], v107 offset:352
	ds_read_b128 v[84:87], v107 offset:368
	ds_read_b128 v[88:91], v108 offset:352
	ds_read_b128 v[92:95], v108 offset:368
	ds_read_b128 v[96:99], v109 offset:352
	ds_read_b128 v[100:103], v109 offset:368
	v_cmp_lt_u32_e32 vcc, 11, v110
	s_waitcnt lgkmcnt(6)
	s_mov_b64 exec, vcc
	v_pk_add_f32 v[40:41], v[40:41], v[72:73]
	v_pk_add_f32 v[42:43], v[42:43], v[74:75]
	v_pk_add_f32 v[44:45], v[44:45], v[76:77]
	v_pk_add_f32 v[46:47], v[46:47], v[78:79]
	s_waitcnt lgkmcnt(4)
	v_pk_add_f32 v[48:49], v[48:49], v[80:81]
	v_pk_add_f32 v[50:51], v[50:51], v[82:83]
	v_pk_add_f32 v[52:53], v[52:53], v[84:85]
	v_pk_add_f32 v[54:55], v[54:55], v[86:87]
	s_waitcnt lgkmcnt(2)
	v_pk_add_f32 v[56:57], v[56:57], v[88:89]
	v_pk_add_f32 v[58:59], v[58:59], v[90:91]
	v_pk_add_f32 v[60:61], v[60:61], v[92:93]
	v_pk_add_f32 v[62:63], v[62:63], v[94:95]
	s_waitcnt lgkmcnt(0)
	v_pk_add_f32 v[64:65], v[64:65], v[96:97]
	v_pk_add_f32 v[66:67], v[66:67], v[98:99]
	v_pk_add_f32 v[68:69], v[68:69], v[100:101]
	v_pk_add_f32 v[70:71], v[70:71], v[102:103]
	s_mov_b64 exec, -1
	ds_read_b128 v[72:75], v106 offset:384
	ds_read_b128 v[76:79], v106 offset:400
	ds_read_b128 v[80:83], v107 offset:384
	ds_read_b128 v[84:87], v107 offset:400
	ds_read_b128 v[88:91], v108 offset:384
	ds_read_b128 v[92:95], v108 offset:400
	ds_read_b128 v[96:99], v109 offset:384
	ds_read_b128 v[100:103], v109 offset:400
	v_cmp_lt_u32_e32 vcc, 12, v110
	s_waitcnt lgkmcnt(6)
	s_mov_b64 exec, vcc
	v_pk_add_f32 v[40:41], v[40:41], v[72:73]
	v_pk_add_f32 v[42:43], v[42:43], v[74:75]
	v_pk_add_f32 v[44:45], v[44:45], v[76:77]
	v_pk_add_f32 v[46:47], v[46:47], v[78:79]
	s_waitcnt lgkmcnt(4)
	v_pk_add_f32 v[48:49], v[48:49], v[80:81]
	v_pk_add_f32 v[50:51], v[50:51], v[82:83]
	v_pk_add_f32 v[52:53], v[52:53], v[84:85]
	v_pk_add_f32 v[54:55], v[54:55], v[86:87]
	s_waitcnt lgkmcnt(2)
	v_pk_add_f32 v[56:57], v[56:57], v[88:89]
	v_pk_add_f32 v[58:59], v[58:59], v[90:91]
	v_pk_add_f32 v[60:61], v[60:61], v[92:93]
	v_pk_add_f32 v[62:63], v[62:63], v[94:95]
	s_waitcnt lgkmcnt(0)
; #define LAS __attribute__((address_space(3)))
; __device__ void boxfilter_unit(const Params& p, LAS unsigned char* lds, int u) {
;     ...
;     for (int i = 0; i < 4; ++i) { const int tok = tid + 512 * i; const int r = tok >> 6, c = tok & 63; const int lo = max(c - hw, 0), hi = min(c + hw, 64);
;         f32x4 s0 = (f32x4){0.f, 0.f, 0.f, 0.f}, s1 = s0;
;         for (int cc = lo; cc < hi; ++cc) { s0 += *(const LAS f32x4*)(Y + (r * 64 + cc) * 8); s1 += *(const LAS f32x4*)(Y + (r * 64 + cc) * 8 + 4); }
	v_pk_add_f32 v[64:65], v[64:65], v[96:97]
	v_pk_add_f32 v[66:67], v[66:67], v[98:99]
	v_pk_add_f32 v[68:69], v[68:69], v[100:101]
	v_pk_add_f32 v[70:71], v[70:71], v[102:103]
	s_mov_b64 exec, -1
	ds_read_b128 v[72:75], v106 offset:416
	ds_read_b128 v[76:79], v106 offset:432
	ds_read_b128 v[80:83], v107 offset:416
	ds_read_b128 v[84:87], v107 offset:432
	ds_read_b128 v[88:91], v108 offset:416
	ds_read_b128 v[92:95], v108 offset:432
	ds_read_b128 v[96:99], v109 offset:416
	ds_read_b128 v[100:103], v109 offset:432
	v_cmp_lt_u32_e32 vcc, 13, v110
	s_waitcnt lgkmcnt(6)
	s_mov_b64 exec, vcc
	v_pk_add_f32 v[40:41], v[40:41], v[72:73]
	v_pk_add_f32 v[42:43], v[42:43], v[74:75]
	v_pk_add_f32 v[44:45], v[44:45], v[76:77]
	v_pk_add_f32 v[46:47], v[46:47], v[78:79]
	s_waitcnt lgkmcnt(4)
	v_pk_add_f32 v[48:49], v[48:49], v[80:81]
	v_pk_add_f32 v[50:51], v[50:51], v[82:83]
	v_pk_add_f32 v[52:53], v[52:53], v[84:85]
	v_pk_add_f32 v[54:55], v[54:55], v[86:87]
	s_waitcnt lgkmcnt(2)
	v_pk_add_f32 v[56:57], v[56:57], v[88:89]
	v_pk_add_f32 v[58:59], v[58:59], v[90:91]
	v_pk_add_f32 v[60:61], v[60:61], v[92:93]
	v_pk_add_f32 v[62:63], v[62:63], v[94:95]
	s_waitcnt lgkmcnt(0)
	v_pk_add_f32 v[64:65], v[64:65], v[96:97]
	v_pk_add_f32 v[66:67], v[66:67], v[98:99]
	v_pk_add_f32 v[68:69], v[68:69], v[100:101]
	v_pk_add_f32 v[70:71], v[70:71], v[102:103]
	s_mov_b64 exec, -1
	ds_read_b128 v[72:75], v106 offset:448
	ds_read_b128 v[76:79], v106 offset:464
	ds_read_b128 v[80:83], v107 offset:448
	ds_read_b128 v[84:87], v107 offset:464
	ds_read_b128 v[88:91], v108 offset:448
	ds_read_b128 v[92:95], v108 offset:464
	ds_read_b128 v[96:99], v109 offset:448
	ds_read_b128 v[100:103], v109 offset:464
	v_cmp_lt_u32_e32 vcc, 14, v110
	s_waitcnt lgkmcnt(6)
	s_mov_b64 exec, vcc
	v_pk_add_f32 v[40:41], v[40:41], v[72:73]
	v_pk_add_f32 v[42:43], v[42:43], v[74:75]
	v_pk_add_f32 v[44:45], v[44:45], v[76:77]
	v_pk_add_f32 v[46:47], v[46:47], v[78:79]
	s_waitcnt lgkmcnt(4)
	v_pk_add_f32 v[48:49], v[48:49], v[80:81]
	v_pk_add_f32 v[50:51], v[50:51], v[82:83]
	v_pk_add_f32 v[52:53], v[52:53], v[84:85]
	v_pk_add_f32 v[54:55], v[54:55], v[86:87]
	s_waitcnt lgkmcnt(2)
	v_pk_add_f32 v[56:57], v[56:57], v[88:89]
	v_pk_add_f32 v[58:59], v[58:59], v[90:91]
	v_pk_add_f32 v[60:61], v[60:61], v[92:93]
	v_pk_add_f32 v[62:63], v[62:63], v[94:95]
	s_waitcnt lgkmcnt(0)
	v_pk_add_f32 v[64:65], v[64:65], v[96:97]
	v_pk_add_f32 v[66:67], v[66:67], v[98:99]
	v_pk_add_f32 v[68:69], v[68:69], v[100:101]
	v_pk_add_f32 v[70:71], v[70:71], v[102:103]
	s_mov_b64 exec, -1
	ds_read_b128 v[72:75], v106 offset:480
	ds_read_b128 v[76:79], v106 offset:496
	ds_read_b128 v[80:83], v107 offset:480
	ds_read_b128 v[84:87], v107 offset:496
	ds_read_b128 v[88:91], v108 offset:480
	ds_read_b128 v[92:95], v108 offset:496
	ds_read_b128 v[96:99], v109 offset:480
	ds_read_b128 v[100:103], v109 offset:496
	v_cmp_lt_u32_e32 vcc, 15, v110
	s_waitcnt lgkmcnt(6)
	s_mov_b64 exec, vcc
	v_pk_add_f32 v[40:41], v[40:41], v[72:73]
	v_pk_add_f32 v[42:43], v[42:43], v[74:75]
	v_pk_add_f32 v[44:45], v[44:45], v[76:77]
	v_pk_add_f32 v[46:47], v[46:47], v[78:79]
	s_waitcnt lgkmcnt(4)
	v_pk_add_f32 v[48:49], v[48:49], v[80:81]
	v_pk_add_f32 v[50:51], v[50:51], v[82:83]
	v_pk_add_f32 v[52:53], v[52:53], v[84:85]
	v_pk_add_f32 v[54:55], v[54:55], v[86:87]
	s_waitcnt lgkmcnt(2)
	v_pk_add_f32 v[56:57], v[56:57], v[88:89]
	v_pk_add_f32 v[58:59], v[58:59], v[90:91]
	v_pk_add_f32 v[60:61], v[60:61], v[92:93]
	v_pk_add_f32 v[62:63], v[62:63], v[94:95]
	s_waitcnt lgkmcnt(0)
	v_pk_add_f32 v[64:65], v[64:65], v[96:97]
	v_pk_add_f32 v[66:67], v[66:67], v[98:99]
	v_pk_add_f32 v[68:69], v[68:69], v[100:101]
	v_pk_add_f32 v[70:71], v[70:71], v[102:103]
; #define LAS __attribute__((address_space(3)))
; __device__ __forceinline__ unsigned cvt_pk_bf16(float lo, float hi) { unsigned r; asm volatile("v_cvt_pk_bf16_f32 %0, %1, %2" : "=v"(r) : "v"(lo), "v"(hi)); return r; }
; __device__ void boxfilter_unit(const Params& p, LAS unsigned char* lds, int u) {
;     ...
;         const float cnt = (float)(hi - lo);
;         const f32x4 m0 = s0 / cnt - *(const LAS f32x4*)(X + tok * 8), m1 = s1 / cnt - *(const LAS f32x4*)(X + tok * 8 + 4);
;         u32x4 w; w.x = cvt_pk_bf16(m0[0], m0[1]); w.y = cvt_pk_bf16(m0[2], m0[3]); w.z = cvt_pk_bf16(m1[0], m1[1]); w.w = cvt_pk_bf16(m1[2], m1[3]);
;         *(u32x4*)(dst + (size_t)tok * 512) = w; }
;     __syncthreads();
; }
; __device__ __forceinline__ void run_phase(const Params& p, LAS unsigned char* lds, int ph) {
;     ...
;           boxfilter_unit(p, lds, G * 4 + mem); boxfilter_unit(p, lds, (127 - G) * 4 + mem); }
.Lbox_p2_done:
	s_mov_b64 exec, -1
	ds_read_b128 v[72:75], v12
	ds_read_b128 v[76:79], v12 offset:16
	ds_read_b128 v[80:83], v12 offset:16384
	ds_read_b128 v[84:87], v12 offset:16400
	ds_read_b128 v[88:91], v12 offset:32768
	ds_read_b128 v[92:95], v12 offset:32784
	ds_read_b128 v[96:99], v12 offset:49152
	ds_read_b128 v[100:103], v12 offset:49168
	v_cvt_f32_i32_e32 v112, v110
	v_rcp_f32_e32 v113, v112
	s_nop 0
	v_fma_f32 v114, -v112, v113, 1.0
	v_fmac_f32_e32 v113, v114, v113
	v_fma_f32 v114, -v112, v113, 1.0
	v_fmac_f32_e32 v113, v114, v113
	v_mul_f32_e32 v115, v40, v113
	v_fma_f32 v116, -v112, v115, v40
	v_fma_f32 v40, v116, v113, v115
	v_mul_f32_e32 v115, v41, v113
	v_fma_f32 v116, -v112, v115, v41
	v_fma_f32 v41, v116, v113, v115
	v_mul_f32_e32 v115, v42, v113
	v_fma_f32 v116, -v112, v115, v42
	v_fma_f32 v42, v116, v113, v115
	v_mul_f32_e32 v115, v43, v113
	v_fma_f32 v116, -v112, v115, v43
	v_fma_f32 v43, v116, v113, v115
	v_mul_f32_e32 v115, v44, v113
	v_fma_f32 v116, -v112, v115, v44
	v_fma_f32 v44, v116, v113, v115
	v_mul_f32_e32 v115, v45, v113
	v_fma_f32 v116, -v112, v115, v45
	v_fma_f32 v45, v116, v113, v115
	v_mul_f32_e32 v115, v46, v113
	v_fma_f32 v116, -v112, v115, v46
	v_fma_f32 v46, v116, v113, v115
	v_mul_f32_e32 v115, v47, v113
	v_fma_f32 v116, -v112, v115, v47
	v_fma_f32 v47, v116, v113, v115
	v_mul_f32_e32 v115, v48, v113
	v_fma_f32 v116, -v112, v115, v48
	v_fma_f32 v48, v116, v113, v115
	v_mul_f32_e32 v115, v49, v113
	v_fma_f32 v116, -v112, v115, v49
	v_fma_f32 v49, v116, v113, v115
	v_mul_f32_e32 v115, v50, v113
	v_fma_f32 v116, -v112, v115, v50
	v_fma_f32 v50, v116, v113, v115
	v_mul_f32_e32 v115, v51, v113
	v_fma_f32 v116, -v112, v115, v51
	v_fma_f32 v51, v116, v113, v115
	v_mul_f32_e32 v115, v52, v113
	v_fma_f32 v116, -v112, v115, v52
	v_fma_f32 v52, v116, v113, v115
	v_mul_f32_e32 v115, v53, v113
	v_fma_f32 v116, -v112, v115, v53
	v_fma_f32 v53, v116, v113, v115
	v_mul_f32_e32 v115, v54, v113
	v_fma_f32 v116, -v112, v115, v54
	v_fma_f32 v54, v116, v113, v115
	v_mul_f32_e32 v115, v55, v113
	v_fma_f32 v116, -v112, v115, v55
	v_fma_f32 v55, v116, v113, v115
	v_mul_f32_e32 v115, v56, v113
	v_fma_f32 v116, -v112, v115, v56
	v_fma_f32 v56, v116, v113, v115
	v_mul_f32_e32 v115, v57, v113
	v_fma_f32 v116, -v112, v115, v57
	v_fma_f32 v57, v116, v113, v115
	v_mul_f32_e32 v115, v58, v113
	v_fma_f32 v116, -v112, v115, v58
	v_fma_f32 v58, v116, v113, v115
	v_mul_f32_e32 v115, v59, v113
	v_fma_f32 v116, -v112, v115, v59
	v_fma_f32 v59, v116, v113, v115
	v_mul_f32_e32 v115, v60, v113
	v_fma_f32 v116, -v112, v115, v60
	v_fma_f32 v60, v116, v113, v115
	v_mul_f32_e32 v115, v61, v113
	v_fma_f32 v116, -v112, v115, v61
	v_fma_f32 v61, v116, v113, v115
	v_mul_f32_e32 v115, v62, v113
	v_fma_f32 v116, -v112, v115, v62
	v_fma_f32 v62, v116, v113, v115
	v_mul_f32_e32 v115, v63, v113
	v_fma_f32 v116, -v112, v115, v63
	v_fma_f32 v63, v116, v113, v115
	v_mul_f32_e32 v115, v64, v113
	v_fma_f32 v116, -v112, v115, v64
	v_fma_f32 v64, v116, v113, v115
	v_mul_f32_e32 v115, v65, v113
	v_fma_f32 v116, -v112, v115, v65
	v_fma_f32 v65, v116, v113, v115
	v_mul_f32_e32 v115, v66, v113
	v_fma_f32 v116, -v112, v115, v66
	v_fma_f32 v66, v116, v113, v115
	v_mul_f32_e32 v115, v67, v113
	v_fma_f32 v116, -v112, v115, v67
	v_fma_f32 v67, v116, v113, v115
	v_mul_f32_e32 v115, v68, v113
	v_fma_f32 v116, -v112, v115, v68
	v_fma_f32 v68, v116, v113, v115
	v_mul_f32_e32 v115, v69, v113
	v_fma_f32 v116, -v112, v115, v69
	v_fma_f32 v69, v116, v113, v115
	v_mul_f32_e32 v115, v70, v113
	v_fma_f32 v116, -v112, v115, v70
	v_fma_f32 v70, v116, v113, v115
	v_mul_f32_e32 v115, v71, v113
	v_fma_f32 v116, -v112, v115, v71
	v_fma_f32 v71, v116, v113, v115
	s_waitcnt lgkmcnt(6)
	v_sub_f32_e32 v40, v40, v72
	v_sub_f32_e32 v41, v41, v73
	v_sub_f32_e32 v42, v42, v74
	v_sub_f32_e32 v43, v43, v75
	v_sub_f32_e32 v44, v44, v76
	v_sub_f32_e32 v45, v45, v77
	v_sub_f32_e32 v46, v46, v78
	v_sub_f32_e32 v47, v47, v79
	v_cvt_pk_bf16_f32 v120, v40, v41
	v_cvt_pk_bf16_f32 v121, v42, v43
	v_cvt_pk_bf16_f32 v122, v44, v45
	v_cvt_pk_bf16_f32 v123, v46, v47
	global_store_dwordx4 v136, v[120:123], s[28:29]
	s_waitcnt lgkmcnt(4)
	v_sub_f32_e32 v48, v48, v80
	v_sub_f32_e32 v49, v49, v81
	v_sub_f32_e32 v50, v50, v82
	v_sub_f32_e32 v51, v51, v83
	v_sub_f32_e32 v52, v52, v84
	v_sub_f32_e32 v53, v53, v85
	v_sub_f32_e32 v54, v54, v86
	v_sub_f32_e32 v55, v55, v87
	v_cvt_pk_bf16_f32 v124, v48, v49
	v_cvt_pk_bf16_f32 v125, v50, v51
	v_cvt_pk_bf16_f32 v126, v52, v53
	v_cvt_pk_bf16_f32 v127, v54, v55
	global_store_dwordx4 v137, v[124:127], s[28:29]
	s_waitcnt lgkmcnt(2)
	v_sub_f32_e32 v56, v56, v88
	v_sub_f32_e32 v57, v57, v89
	v_sub_f32_e32 v58, v58, v90
	v_sub_f32_e32 v59, v59, v91
	v_sub_f32_e32 v60, v60, v92
	v_sub_f32_e32 v61, v61, v93
	v_sub_f32_e32 v62, v62, v94
	v_sub_f32_e32 v63, v63, v95
	v_cvt_pk_bf16_f32 v128, v56, v57
	v_cvt_pk_bf16_f32 v129, v58, v59
	v_cvt_pk_bf16_f32 v130, v60, v61
	v_cvt_pk_bf16_f32 v131, v62, v63
	global_store_dwordx4 v138, v[128:131], s[28:29]
	s_waitcnt lgkmcnt(0)
	v_sub_f32_e32 v64, v64, v96
	v_sub_f32_e32 v65, v65, v97
	v_sub_f32_e32 v66, v66, v98
	v_sub_f32_e32 v67, v67, v99
	v_sub_f32_e32 v68, v68, v100
	v_sub_f32_e32 v69, v69, v101
	v_sub_f32_e32 v70, v70, v102
	v_sub_f32_e32 v71, v71, v103
	v_cvt_pk_bf16_f32 v132, v64, v65
	v_cvt_pk_bf16_f32 v133, v66, v67
	v_cvt_pk_bf16_f32 v134, v68, v69
	v_cvt_pk_bf16_f32 v135, v70, v71
	global_store_dwordx4 v139, v[132:135], s[28:29]
	s_add_u32 s7, s7, 1
	s_cmp_lt_u32 s7, 2
	s_cbranch_scc1 .Lbox_unit
	s_mov_b32 s0, 0x40000
	v_lshl_add_u32 v0, s2, 9, v104
	v_cmp_gt_i32_e32 vcc, s0, v0
	s_barrier
	s_and_saveexec_b64 s[0:1], vcc
	s_cbranch_execz .LBB0_471
	v_ashrrev_i32_e32 v1, 31, v0
	v_lshl_add_u64 v[2:3], v[0:1], 1, s[70:71]
	s_mov_b64 s[4:5], 0x2000000
	v_and_b32_e32 v6, 0x7f, v104
	v_lshl_add_u64 v[2:3], v[2:3], 0, s[4:5]
	s_mov_b64 s[4:5], 0
	v_mov_b32_e32 v5, 0
	s_mov_b64 s[6:7], 0x40000
	s_mov_b32 s3, 0x1ffff
	s_branch .LBB0_469
